# final-norm gamma loads hoisted out of row loop + GLU epilogue loads software-pipelined one iteration ahead (counted vmcnt(5))
# speedup vs baseline: 1.0035x; 1.0035x over previous
.LBB0_916:
	v_lshl_or_b32 v130, s7, 8, v152
	v_lshl_add_u32 v154, s8, 8, v150
	v_mov_b64_e32 v[144:145], s[82:83]
	v_ashrrev_i32_e32 v131, 31, v130
	v_mad_i64_i32 v[128:129], s[0:1], v154, s14, v[144:145]
	v_lshlrev_b64 v[146:147], 1, v[130:131]
	v_lshl_add_u64 v[148:149], v[128:129], 0, v[146:147]
	v_add_co_u32_e32 v128, vcc, 0x1000, v148
	v_lshl_add_u64 v[142:143], v[130:131], 2, s[72:73]
	s_nop 0
	v_addc_co_u32_e32 v129, vcc, 0, v149, vcc
	global_load_dwordx4 v[156:159], v[128:129], off
	global_load_dwordx4 v[160:163], v[148:149], off
	global_load_dwordx4 v[164:167], v[142:143], off offset:16
	global_load_dwordx4 v[168:171], v[142:143], off
	global_load_dwordx4 v[176:179], v[128:129], off offset:256
	global_load_dwordx4 v[180:183], v[148:149], off offset:256
	global_load_dwordx4 v[184:187], v[142:143], off offset:528
	global_load_dwordx4 v[208:211], v[142:143], off offset:512
	s_waitcnt vmcnt(4)
	v_pk_add_f32 v[130:131], v[122:123], v[166:167]
	v_pk_add_f32 v[124:125], v[124:125], v[168:169]
	v_pk_add_f32 v[122:123], v[120:121], v[164:165]
	v_mul_f32_e32 v120, 0xbfb8aa3b, v124
	v_mul_f32_e32 v121, 0xbfb8aa3b, v125
	v_exp_f32_e32 v120, v120
	v_exp_f32_e32 v121, v121
	v_lshlrev_b32_e32 v164, 16, v156
	v_and_b32_e32 v165, 0xffff0000, v156
	v_lshlrev_b32_e32 v155, 16, v160
	v_pk_add_f32 v[120:121], v[120:121], 1.0 op_sel_hi:[1,0]
	v_and_b32_e32 v160, 0xffff0000, v160
	v_rcp_f32_e32 v156, v121
	v_mul_f32_e32 v124, 0xbfb8aa3b, v155
	v_exp_f32_e32 v124, v124
	v_pk_add_f32 v[126:127], v[126:127], v[170:171]
	v_mul_f32_e32 v125, 1.0, v156
	v_mov_b32_e32 v121, v125
	v_rcp_f32_e32 v156, v120
	v_mul_f32_e32 v122, 0xbfb8aa3b, v122
	v_mul_f32_e32 v123, 0xbfb8aa3b, v123
	v_exp_f32_e32 v122, v122
	v_mul_f32_e32 v125, 1.0, v156
	v_mov_b32_e32 v120, v125
	v_mul_f32_e32 v125, 0xbfb8aa3b, v160
	v_exp_f32_e32 v125, v125
	v_pk_mul_f32 v[120:121], v[120:121], v[164:165]
	v_exp_f32_e32 v123, v123
	v_pk_add_f32 v[124:125], v[124:125], 1.0 op_sel_hi:[1,0]
	s_nop 0
	v_rcp_f32_e32 v164, v125
	v_pk_add_f32 v[122:123], v[122:123], 1.0 op_sel_hi:[1,0]
	v_mul_f32_e32 v156, v160, v164
	v_mov_b32_e32 v125, v156
	v_rcp_f32_e32 v160, v124
	s_nop 0
	v_mul_f32_e32 v156, v155, v160
	v_mov_b32_e32 v124, v156
	v_pk_mul_f32 v[120:121], v[124:125], v[120:121]
	v_and_b32_e32 v155, 0xffff0000, v161
	v_cvt_pk_bf16_f32 v120, v120, v121
	v_mul_f32_e32 v121, 0xbfb8aa3b, v126
	v_exp_f32_e32 v124, v121
	v_mul_f32_e32 v121, 0xbfb8aa3b, v127
	v_exp_f32_e32 v125, v121
	v_lshlrev_b32_e32 v121, 16, v161
	v_mul_f32_e32 v126, 0xbfb8aa3b, v121
	v_exp_f32_e32 v126, v126
	v_pk_add_f32 v[124:125], v[124:125], 1.0 op_sel_hi:[1,0]
	v_lshlrev_b32_e32 v156, 16, v157
	v_rcp_f32_e32 v160, v125
	v_and_b32_e32 v157, 0xffff0000, v157
	v_mul_f32_e32 v127, 1.0, v160
	v_mov_b32_e32 v125, v127
	v_rcp_f32_e32 v160, v124
	s_nop 0
	v_mul_f32_e32 v127, 1.0, v160
	v_mov_b32_e32 v124, v127
	v_mul_f32_e32 v127, 0xbfb8aa3b, v155
	v_exp_f32_e32 v127, v127
	v_pk_mul_f32 v[124:125], v[124:125], v[156:157]
	v_pk_add_f32 v[126:127], v[126:127], 1.0 op_sel_hi:[1,0]
	s_nop 0
	v_rcp_f32_e32 v157, v127
	s_nop 0
	v_mul_f32_e32 v156, v155, v157
	v_mov_b32_e32 v127, v156
	v_rcp_f32_e32 v156, v126
	s_nop 0
	v_mul_f32_e32 v155, v121, v156
	v_mov_b32_e32 v126, v155
	v_pk_mul_f32 v[124:125], v[126:127], v[124:125]
	v_lshlrev_b32_e32 v126, 16, v158
	v_cvt_pk_bf16_f32 v121, v124, v125
	v_rcp_f32_e32 v157, v123
	v_and_b32_e32 v127, 0xffff0000, v158
	v_lshlrev_b32_e32 v155, 16, v162
	v_and_b32_e32 v156, 0xffff0000, v162
	v_mul_f32_e32 v125, 1.0, v157
	v_mov_b32_e32 v123, v125
	v_rcp_f32_e32 v157, v122
	v_mul_f32_e32 v124, 0xbfb8aa3b, v155
	v_exp_f32_e32 v124, v124
	v_mul_f32_e32 v125, 1.0, v157
	v_mov_b32_e32 v122, v125
	v_mul_f32_e32 v125, 0xbfb8aa3b, v156
	v_exp_f32_e32 v125, v125
	v_pk_mul_f32 v[122:123], v[122:123], v[126:127]
	v_pk_add_f32 v[124:125], v[124:125], 1.0 op_sel_hi:[1,0]
	s_nop 0
	v_rcp_f32_e32 v127, v125
	s_nop 0
	v_mul_f32_e32 v126, v156, v127
	v_mov_b32_e32 v125, v126
	v_rcp_f32_e32 v127, v124
	s_nop 0
	v_mul_f32_e32 v126, v155, v127
	v_mov_b32_e32 v124, v126
	v_pk_mul_f32 v[122:123], v[124:125], v[122:123]
	v_and_b32_e32 v155, 0xffff0000, v163
	v_cvt_pk_bf16_f32 v122, v122, v123
	v_mul_f32_e32 v123, 0xbfb8aa3b, v130
	v_exp_f32_e32 v124, v123
	v_mul_f32_e32 v123, 0xbfb8aa3b, v131
	v_exp_f32_e32 v125, v123
	v_lshlrev_b32_e32 v130, 16, v159
	v_and_b32_e32 v131, 0xffff0000, v159
	v_lshlrev_b32_e32 v123, 16, v163
	v_pk_add_f32 v[124:125], v[124:125], 1.0 op_sel_hi:[1,0]
	v_mul_f32_e32 v126, 0xbfb8aa3b, v123
	v_rcp_f32_e32 v156, v125
	v_exp_f32_e32 v126, v126
	v_mul_f32_e32 v127, 1.0, v156
	v_mov_b32_e32 v125, v127
	v_rcp_f32_e32 v156, v124
	s_nop 0
	v_mul_f32_e32 v127, 1.0, v156
	v_mov_b32_e32 v124, v127
	v_mul_f32_e32 v127, 0xbfb8aa3b, v155
	v_exp_f32_e32 v127, v127
	v_pk_mul_f32 v[124:125], v[124:125], v[130:131]
	v_pk_add_f32 v[126:127], v[126:127], 1.0 op_sel_hi:[1,0]
	s_nop 0
	v_rcp_f32_e32 v131, v127
	s_nop 0
	v_mul_f32_e32 v130, v155, v131
	v_mov_b32_e32 v127, v130
	v_rcp_f32_e32 v131, v126
	s_nop 0
	v_mul_f32_e32 v130, v123, v131
	v_mov_b32_e32 v126, v130
	v_pk_mul_f32 v[124:125], v[126:127], v[124:125]
	s_nop 0
	v_cvt_pk_bf16_f32 v123, v124, v125
	global_store_dwordx4 v[148:149], v[120:123], off
	s_nop 1
	v_or_b32_e32 v248, 16, v154
	v_mad_i64_i32 v[248:249], s[0:1], v248, s14, v[144:145]
	v_lshl_add_u64 v[250:251], v[248:249], 0, v[146:147]
	v_add_co_u32_e32 v174, vcc, s15, v250
	s_nop 1
	v_addc_co_u32_e32 v175, vcc, 0, v251, vcc
	global_load_dwordx4 v[228:231], v[174:175], off
	global_load_dwordx4 v[232:235], v[250:251], off
	global_load_dwordx4 v[236:239], v[142:143], off offset:16
	global_load_dwordx4 v[240:243], v[142:143], off
	s_waitcnt vmcnt(5)
	v_lshlrev_b32_e32 v155, 16, v180
	v_and_b32_e32 v124, 0xffff0000, v180
	v_pk_add_f32 v[156:157], v[116:117], v[208:209]
	v_pk_add_f32 v[116:117], v[114:115], v[186:187]
	v_pk_add_f32 v[114:115], v[112:113], v[184:185]
	v_mul_f32_e32 v112, 0xbfb8aa3b, v156
	v_mul_f32_e32 v113, 0xbfb8aa3b, v157
	v_exp_f32_e32 v112, v112
	v_exp_f32_e32 v113, v113
	v_lshlrev_b32_e32 v130, 16, v176
	v_and_b32_e32 v131, 0xffff0000, v176
	v_pk_add_f32 v[118:119], v[118:119], v[210:211]
	v_pk_add_f32 v[112:113], v[112:113], 1.0 op_sel_hi:[1,0]
	v_mul_f32_e32 v128, 0xbfb8aa3b, v155
	v_rcp_f32_e32 v129, v113
	v_exp_f32_e32 v128, v128
	v_mul_f32_e32 v114, 0xbfb8aa3b, v114
	v_mul_f32_e32 v115, 0xbfb8aa3b, v115
	v_mul_f32_e32 v120, 1.0, v129
	v_mov_b32_e32 v113, v120
	v_rcp_f32_e32 v129, v112
	v_exp_f32_e32 v114, v114
	v_exp_f32_e32 v115, v115
	v_mul_f32_e32 v120, 1.0, v129
	v_mov_b32_e32 v112, v120
	v_mul_f32_e32 v120, 0xbfb8aa3b, v124
	v_exp_f32_e32 v129, v120
	v_pk_mul_f32 v[112:113], v[112:113], v[130:131]
	v_pk_add_f32 v[114:115], v[114:115], 1.0 op_sel_hi:[1,0]
	v_pk_add_f32 v[128:129], v[128:129], 1.0 op_sel_hi:[1,0]
	s_nop 0
	v_rcp_f32_e32 v130, v129
	s_nop 0
	v_mul_f32_e32 v120, v124, v130
	v_mov_b32_e32 v129, v120
	v_rcp_f32_e32 v124, v128
	s_nop 0
	v_mul_f32_e32 v120, v155, v124
	v_mov_b32_e32 v128, v120
	v_pk_mul_f32 v[112:113], v[128:129], v[112:113]
	v_and_b32_e32 v128, 0xffff0000, v181
	v_cvt_pk_bf16_f32 v112, v112, v113
	v_mul_f32_e32 v113, 0xbfb8aa3b, v118
	v_exp_f32_e32 v118, v113
	v_mul_f32_e32 v113, 0xbfb8aa3b, v119
	v_exp_f32_e32 v119, v113
	v_lshlrev_b32_e32 v113, 16, v181
	v_lshlrev_b32_e32 v124, 16, v177
	v_and_b32_e32 v125, 0xffff0000, v177
	v_pk_add_f32 v[118:119], v[118:119], 1.0 op_sel_hi:[1,0]
	v_mul_f32_e32 v120, 0xbfb8aa3b, v113
	v_rcp_f32_e32 v129, v119
	v_exp_f32_e32 v120, v120
	v_mul_f32_e32 v121, 1.0, v129
	v_mov_b32_e32 v119, v121
	v_rcp_f32_e32 v129, v118
	s_nop 0
	v_mul_f32_e32 v121, 1.0, v129
	v_mov_b32_e32 v118, v121
	v_mul_f32_e32 v121, 0xbfb8aa3b, v128
	v_exp_f32_e32 v121, v121
	v_pk_mul_f32 v[118:119], v[118:119], v[124:125]
	v_pk_add_f32 v[120:121], v[120:121], 1.0 op_sel_hi:[1,0]
	s_nop 0
	v_rcp_f32_e32 v125, v121
	s_nop 0
	v_mul_f32_e32 v124, v128, v125
	v_mov_b32_e32 v121, v124
	v_rcp_f32_e32 v125, v120
	s_nop 0
	v_mul_f32_e32 v124, v113, v125
	v_mov_b32_e32 v120, v124
	v_pk_mul_f32 v[118:119], v[120:121], v[118:119]
	v_lshlrev_b32_e32 v120, 16, v178
	v_cvt_pk_bf16_f32 v113, v118, v119
	v_and_b32_e32 v121, 0xffff0000, v178
	v_rcp_f32_e32 v122, v115
	v_lshlrev_b32_e32 v124, 16, v182
	v_and_b32_e32 v125, 0xffff0000, v182
	v_mul_f32_e32 v118, 0xbfb8aa3b, v124
	v_mul_f32_e32 v119, 1.0, v122
	v_mov_b32_e32 v115, v119
	v_rcp_f32_e32 v122, v114
	v_exp_f32_e32 v118, v118
	v_mul_f32_e32 v119, 1.0, v122
	v_mov_b32_e32 v114, v119
	v_mul_f32_e32 v119, 0xbfb8aa3b, v125
	v_exp_f32_e32 v119, v119
	v_pk_mul_f32 v[114:115], v[114:115], v[120:121]
	v_pk_add_f32 v[118:119], v[118:119], 1.0 op_sel_hi:[1,0]
	s_nop 0
	v_rcp_f32_e32 v121, v119
	s_nop 0
	v_mul_f32_e32 v120, v125, v121
	v_mov_b32_e32 v119, v120
	v_rcp_f32_e32 v121, v118
	s_nop 0
	v_mul_f32_e32 v120, v124, v121
	v_mov_b32_e32 v118, v120
	v_pk_mul_f32 v[114:115], v[118:119], v[114:115]
	v_lshlrev_b32_e32 v120, 16, v179
	v_cvt_pk_bf16_f32 v114, v114, v115
	v_mul_f32_e32 v115, 0xbfb8aa3b, v116
	v_exp_f32_e32 v116, v115
	v_mul_f32_e32 v115, 0xbfb8aa3b, v117
	v_exp_f32_e32 v117, v115
	v_and_b32_e32 v121, 0xffff0000, v179
	v_lshlrev_b32_e32 v115, 16, v183
	v_and_b32_e32 v122, 0xffff0000, v183
	v_pk_add_f32 v[116:117], v[116:117], 1.0 op_sel_hi:[1,0]
	v_mul_f32_e32 v118, 0xbfb8aa3b, v115
	v_rcp_f32_e32 v123, v117
	v_exp_f32_e32 v118, v118
	v_mul_f32_e32 v119, 1.0, v123
	v_mov_b32_e32 v117, v119
	v_rcp_f32_e32 v123, v116
	s_nop 0
	v_mul_f32_e32 v119, 1.0, v123
	v_mov_b32_e32 v116, v119
	v_mul_f32_e32 v119, 0xbfb8aa3b, v122
	v_exp_f32_e32 v119, v119
	v_pk_mul_f32 v[116:117], v[116:117], v[120:121]
	v_pk_add_f32 v[118:119], v[118:119], 1.0 op_sel_hi:[1,0]
	s_nop 0
	v_rcp_f32_e32 v121, v119
	s_nop 0
	v_mul_f32_e32 v120, v122, v121
	v_mov_b32_e32 v119, v120
	v_rcp_f32_e32 v121, v118
	s_nop 0
	v_mul_f32_e32 v120, v115, v121
	v_mov_b32_e32 v118, v120
	v_pk_mul_f32 v[116:117], v[118:119], v[116:117]
	s_nop 0
	v_cvt_pk_bf16_f32 v115, v116, v117
	global_store_dwordx4 v[148:149], v[112:115], off offset:256
	global_load_dwordx4 v[176:179], v[174:175], off offset:256
	global_load_dwordx4 v[180:183], v[250:251], off offset:256
	global_load_dwordx4 v[184:187], v[142:143], off offset:528
	global_load_dwordx4 v[208:211], v[142:143], off offset:512
	s_waitcnt vmcnt(5)
	v_pk_add_f32 v[126:127], v[106:107], v[238:239]
	v_pk_add_f32 v[108:109], v[108:109], v[240:241]
	v_pk_add_f32 v[106:107], v[104:105], v[236:237]
	v_mul_f32_e32 v104, 0xbfb8aa3b, v108
	v_mul_f32_e32 v105, 0xbfb8aa3b, v109
	v_exp_f32_e32 v104, v104
	v_exp_f32_e32 v105, v105
	v_lshlrev_b32_e32 v124, 16, v228
	v_and_b32_e32 v125, 0xffff0000, v228
	v_pk_add_f32 v[110:111], v[110:111], v[242:243]
	v_pk_add_f32 v[104:105], v[104:105], 1.0 op_sel_hi:[1,0]
	v_lshlrev_b32_e32 v128, 16, v232
	v_rcp_f32_e32 v112, v105
	v_and_b32_e32 v116, 0xffff0000, v232
	v_mul_f32_e32 v108, 0xbfb8aa3b, v128
	v_exp_f32_e32 v108, v108
	v_mul_f32_e32 v109, 1.0, v112
	v_mov_b32_e32 v105, v109
	v_rcp_f32_e32 v112, v104
	v_mul_f32_e32 v106, 0xbfb8aa3b, v106
	v_mul_f32_e32 v107, 0xbfb8aa3b, v107
	v_exp_f32_e32 v106, v106
	v_mul_f32_e32 v109, 1.0, v112
	v_mov_b32_e32 v104, v109
	v_mul_f32_e32 v109, 0xbfb8aa3b, v116
	v_exp_f32_e32 v109, v109
	v_pk_mul_f32 v[104:105], v[104:105], v[124:125]
	v_exp_f32_e32 v107, v107
	v_pk_add_f32 v[108:109], v[108:109], 1.0 op_sel_hi:[1,0]
	s_nop 0
	v_rcp_f32_e32 v124, v109
	v_pk_add_f32 v[106:107], v[106:107], 1.0 op_sel_hi:[1,0]
	v_mul_f32_e32 v112, v116, v124
	v_mov_b32_e32 v109, v112
	v_rcp_f32_e32 v116, v108
	s_nop 0
	v_mul_f32_e32 v112, v128, v116
	v_mov_b32_e32 v108, v112
	v_pk_mul_f32 v[104:105], v[108:109], v[104:105]
	v_and_b32_e32 v116, 0xffff0000, v233
	v_cvt_pk_bf16_f32 v104, v104, v105
	v_mul_f32_e32 v105, 0xbfb8aa3b, v110
	v_exp_f32_e32 v108, v105
	v_mul_f32_e32 v105, 0xbfb8aa3b, v111
	v_exp_f32_e32 v109, v105
	v_lshlrev_b32_e32 v105, 16, v233
	v_mul_f32_e32 v110, 0xbfb8aa3b, v105
	v_exp_f32_e32 v110, v110
	v_pk_add_f32 v[108:109], v[108:109], 1.0 op_sel_hi:[1,0]
	v_lshlrev_b32_e32 v112, 16, v229
	v_rcp_f32_e32 v117, v109
	v_and_b32_e32 v113, 0xffff0000, v229
	v_mul_f32_e32 v111, 1.0, v117
	v_mov_b32_e32 v109, v111
	v_rcp_f32_e32 v117, v108
	s_nop 0
	v_mul_f32_e32 v111, 1.0, v117
	v_mov_b32_e32 v108, v111
	v_mul_f32_e32 v111, 0xbfb8aa3b, v116
	v_exp_f32_e32 v111, v111
	v_pk_mul_f32 v[108:109], v[108:109], v[112:113]
	v_pk_add_f32 v[110:111], v[110:111], 1.0 op_sel_hi:[1,0]
	s_nop 0
	v_rcp_f32_e32 v113, v111
	s_nop 0
	v_mul_f32_e32 v112, v116, v113
	v_mov_b32_e32 v111, v112
	v_rcp_f32_e32 v113, v110
	s_nop 0
	v_mul_f32_e32 v112, v105, v113
	v_mov_b32_e32 v110, v112
	v_pk_mul_f32 v[108:109], v[110:111], v[108:109]
	v_lshlrev_b32_e32 v110, 16, v230
	v_cvt_pk_bf16_f32 v105, v108, v109
	v_and_b32_e32 v111, 0xffff0000, v230
	v_rcp_f32_e32 v114, v107
	v_lshlrev_b32_e32 v112, 16, v234
	v_and_b32_e32 v113, 0xffff0000, v234
	v_mul_f32_e32 v108, 0xbfb8aa3b, v112
	v_mul_f32_e32 v109, 1.0, v114
	v_mov_b32_e32 v107, v109
	v_rcp_f32_e32 v114, v106
	v_exp_f32_e32 v108, v108
	v_mul_f32_e32 v109, 1.0, v114
	v_mov_b32_e32 v106, v109
	v_mul_f32_e32 v109, 0xbfb8aa3b, v113
	v_exp_f32_e32 v109, v109
	v_pk_mul_f32 v[106:107], v[106:107], v[110:111]
	v_pk_add_f32 v[108:109], v[108:109], 1.0 op_sel_hi:[1,0]
	s_nop 0
	v_rcp_f32_e32 v111, v109
	s_nop 0
	v_mul_f32_e32 v110, v113, v111
	v_mov_b32_e32 v109, v110
	v_rcp_f32_e32 v111, v108
	s_nop 0
	v_mul_f32_e32 v110, v112, v111
	v_mov_b32_e32 v108, v110
	v_pk_mul_f32 v[106:107], v[108:109], v[106:107]
	v_lshlrev_b32_e32 v112, 16, v231
	v_cvt_pk_bf16_f32 v106, v106, v107
	v_mul_f32_e32 v107, 0xbfb8aa3b, v126
	v_exp_f32_e32 v108, v107
	v_mul_f32_e32 v107, 0xbfb8aa3b, v127
	v_exp_f32_e32 v109, v107
	v_and_b32_e32 v113, 0xffff0000, v231
	v_lshlrev_b32_e32 v107, 16, v235
	v_and_b32_e32 v114, 0xffff0000, v235
	v_pk_add_f32 v[108:109], v[108:109], 1.0 op_sel_hi:[1,0]
	v_mul_f32_e32 v110, 0xbfb8aa3b, v107
	v_rcp_f32_e32 v115, v109
	v_exp_f32_e32 v110, v110
	v_mul_f32_e32 v111, 1.0, v115
	v_mov_b32_e32 v109, v111
	v_rcp_f32_e32 v115, v108
	s_nop 0
	v_mul_f32_e32 v111, 1.0, v115
	v_mov_b32_e32 v108, v111
	v_mul_f32_e32 v111, 0xbfb8aa3b, v114
	v_exp_f32_e32 v111, v111
	v_pk_mul_f32 v[108:109], v[108:109], v[112:113]
	v_pk_add_f32 v[110:111], v[110:111], 1.0 op_sel_hi:[1,0]
	s_nop 0
	v_rcp_f32_e32 v113, v111
	s_nop 0
	v_mul_f32_e32 v112, v114, v113
	v_mov_b32_e32 v111, v112
	v_rcp_f32_e32 v113, v110
	s_nop 0
	v_mul_f32_e32 v112, v107, v113
	v_mov_b32_e32 v110, v112
	v_pk_mul_f32 v[108:109], v[110:111], v[108:109]
	s_nop 0
	v_cvt_pk_bf16_f32 v107, v108, v109
	global_store_dwordx4 v[250:251], v[104:107], off
	s_nop 1
	v_or_b32_e32 v212, 32, v154
	v_mad_i64_i32 v[212:213], s[0:1], v212, s14, v[144:145]
	v_lshl_add_u64 v[214:215], v[212:213], 0, v[146:147]
	v_add_co_u32_e32 v246, vcc, s15, v214
	s_nop 1
	v_addc_co_u32_e32 v247, vcc, 0, v215, vcc
	global_load_dwordx4 v[228:231], v[246:247], off
	global_load_dwordx4 v[232:235], v[214:215], off
	global_load_dwordx4 v[236:239], v[142:143], off offset:16
	global_load_dwordx4 v[240:243], v[142:143], off
	s_waitcnt vmcnt(5)
	v_pk_add_f32 v[116:117], v[100:101], v[208:209]
	v_pk_add_f32 v[100:101], v[98:99], v[186:187]
	v_pk_add_f32 v[98:99], v[96:97], v[184:185]
	v_mul_f32_e32 v96, 0xbfb8aa3b, v116
	v_mul_f32_e32 v97, 0xbfb8aa3b, v117
	v_exp_f32_e32 v96, v96
	v_exp_f32_e32 v97, v97
	v_lshlrev_b32_e32 v114, 16, v176
	v_and_b32_e32 v115, 0xffff0000, v176
	v_pk_add_f32 v[102:103], v[102:103], v[210:211]
	v_pk_add_f32 v[96:97], v[96:97], 1.0 op_sel_hi:[1,0]
	v_lshlrev_b32_e32 v116, 16, v180
	v_rcp_f32_e32 v113, v97
	v_and_b32_e32 v108, 0xffff0000, v180
	v_mul_f32_e32 v112, 0xbfb8aa3b, v116
	v_exp_f32_e32 v112, v112
	v_mul_f32_e32 v104, 1.0, v113
	v_mov_b32_e32 v97, v104
	v_rcp_f32_e32 v113, v96
	v_mul_f32_e32 v98, 0xbfb8aa3b, v98
	v_mul_f32_e32 v99, 0xbfb8aa3b, v99
	v_exp_f32_e32 v98, v98
	v_mul_f32_e32 v104, 1.0, v113
	v_mov_b32_e32 v96, v104
	v_mul_f32_e32 v104, 0xbfb8aa3b, v108
	v_exp_f32_e32 v113, v104
	v_pk_mul_f32 v[96:97], v[96:97], v[114:115]
	v_exp_f32_e32 v99, v99
	v_pk_add_f32 v[112:113], v[112:113], 1.0 op_sel_hi:[1,0]
	s_nop 0
	v_rcp_f32_e32 v114, v113
	v_pk_add_f32 v[98:99], v[98:99], 1.0 op_sel_hi:[1,0]
	v_mul_f32_e32 v104, v108, v114
	v_mov_b32_e32 v113, v104
	v_rcp_f32_e32 v108, v112
	s_nop 0
	v_mul_f32_e32 v104, v116, v108
	v_mov_b32_e32 v112, v104
	v_pk_mul_f32 v[96:97], v[112:113], v[96:97]
	v_and_b32_e32 v112, 0xffff0000, v181
	v_cvt_pk_bf16_f32 v96, v96, v97
	v_mul_f32_e32 v97, 0xbfb8aa3b, v102
	v_exp_f32_e32 v102, v97
	v_mul_f32_e32 v97, 0xbfb8aa3b, v103
	v_exp_f32_e32 v103, v97
	v_lshlrev_b32_e32 v97, 16, v181
	v_lshlrev_b32_e32 v108, 16, v177
	v_and_b32_e32 v109, 0xffff0000, v177
	v_pk_add_f32 v[102:103], v[102:103], 1.0 op_sel_hi:[1,0]
	v_mul_f32_e32 v104, 0xbfb8aa3b, v97
	v_rcp_f32_e32 v113, v103
	v_exp_f32_e32 v104, v104
	v_mul_f32_e32 v105, 1.0, v113
	v_mov_b32_e32 v103, v105
	v_rcp_f32_e32 v113, v102
	s_nop 0
	v_mul_f32_e32 v105, 1.0, v113
	v_mov_b32_e32 v102, v105
	v_mul_f32_e32 v105, 0xbfb8aa3b, v112
	v_exp_f32_e32 v105, v105
	v_pk_mul_f32 v[102:103], v[102:103], v[108:109]
	v_pk_add_f32 v[104:105], v[104:105], 1.0 op_sel_hi:[1,0]
	s_nop 0
	v_rcp_f32_e32 v109, v105
	s_nop 0
	v_mul_f32_e32 v108, v112, v109
	v_mov_b32_e32 v105, v108
	v_rcp_f32_e32 v109, v104
	s_nop 0
	v_mul_f32_e32 v108, v97, v109
	v_mov_b32_e32 v104, v108
	v_pk_mul_f32 v[102:103], v[104:105], v[102:103]
	v_lshlrev_b32_e32 v104, 16, v178
	v_cvt_pk_bf16_f32 v97, v102, v103
	v_and_b32_e32 v105, 0xffff0000, v178
	v_rcp_f32_e32 v106, v99
	v_lshlrev_b32_e32 v108, 16, v182
	v_and_b32_e32 v109, 0xffff0000, v182
	v_mul_f32_e32 v102, 0xbfb8aa3b, v108
	v_mul_f32_e32 v103, 1.0, v106
	v_mov_b32_e32 v99, v103
	v_rcp_f32_e32 v106, v98
	v_exp_f32_e32 v102, v102
	v_mul_f32_e32 v103, 1.0, v106
	v_mov_b32_e32 v98, v103
	v_mul_f32_e32 v103, 0xbfb8aa3b, v109
	v_exp_f32_e32 v103, v103
	v_pk_mul_f32 v[98:99], v[98:99], v[104:105]
	v_pk_add_f32 v[102:103], v[102:103], 1.0 op_sel_hi:[1,0]
	s_nop 0
	v_rcp_f32_e32 v105, v103
	s_nop 0
	v_mul_f32_e32 v104, v109, v105
	v_mov_b32_e32 v103, v104
	v_rcp_f32_e32 v105, v102
	s_nop 0
	v_mul_f32_e32 v104, v108, v105
	v_mov_b32_e32 v102, v104
	v_pk_mul_f32 v[98:99], v[102:103], v[98:99]
	v_lshlrev_b32_e32 v104, 16, v179
	v_cvt_pk_bf16_f32 v98, v98, v99
	v_mul_f32_e32 v99, 0xbfb8aa3b, v100
	v_exp_f32_e32 v100, v99
	v_mul_f32_e32 v99, 0xbfb8aa3b, v101
	v_exp_f32_e32 v101, v99
	v_and_b32_e32 v105, 0xffff0000, v179
	v_lshlrev_b32_e32 v99, 16, v183
	v_and_b32_e32 v106, 0xffff0000, v183
	v_pk_add_f32 v[100:101], v[100:101], 1.0 op_sel_hi:[1,0]
	v_mul_f32_e32 v102, 0xbfb8aa3b, v99
	v_rcp_f32_e32 v107, v101
	v_exp_f32_e32 v102, v102
	v_mul_f32_e32 v103, 1.0, v107
	v_mov_b32_e32 v101, v103
	v_rcp_f32_e32 v107, v100
	s_nop 0
	v_mul_f32_e32 v103, 1.0, v107
	v_mov_b32_e32 v100, v103
	v_mul_f32_e32 v103, 0xbfb8aa3b, v106
	v_exp_f32_e32 v103, v103
	v_pk_mul_f32 v[100:101], v[100:101], v[104:105]
	v_pk_add_f32 v[102:103], v[102:103], 1.0 op_sel_hi:[1,0]
	s_nop 0
	v_rcp_f32_e32 v105, v103
	s_nop 0
	v_mul_f32_e32 v104, v106, v105
	v_mov_b32_e32 v103, v104
	v_rcp_f32_e32 v105, v102
	s_nop 0
	v_mul_f32_e32 v104, v99, v105
	v_mov_b32_e32 v102, v104
	v_pk_mul_f32 v[100:101], v[102:103], v[100:101]
	s_nop 0
	v_cvt_pk_bf16_f32 v99, v100, v101
	global_store_dwordx4 v[250:251], v[96:99], off offset:256
	global_load_dwordx4 v[176:179], v[246:247], off offset:256
	global_load_dwordx4 v[180:183], v[214:215], off offset:256
	global_load_dwordx4 v[184:187], v[142:143], off offset:528
	global_load_dwordx4 v[208:211], v[142:143], off offset:512
	s_waitcnt vmcnt(5)
	v_pk_add_f32 v[110:111], v[90:91], v[238:239]
	v_pk_add_f32 v[92:93], v[92:93], v[240:241]
	v_pk_add_f32 v[90:91], v[88:89], v[236:237]
	v_mul_f32_e32 v88, 0xbfb8aa3b, v92
	v_mul_f32_e32 v89, 0xbfb8aa3b, v93
	v_exp_f32_e32 v88, v88
	v_exp_f32_e32 v89, v89
	v_lshlrev_b32_e32 v108, 16, v228
	v_and_b32_e32 v109, 0xffff0000, v228
	v_pk_add_f32 v[94:95], v[94:95], v[242:243]
	v_pk_add_f32 v[88:89], v[88:89], 1.0 op_sel_hi:[1,0]
	v_lshlrev_b32_e32 v112, 16, v232
	v_rcp_f32_e32 v96, v89
	v_and_b32_e32 v100, 0xffff0000, v232
	v_mul_f32_e32 v92, 0xbfb8aa3b, v112
	v_exp_f32_e32 v92, v92
	v_mul_f32_e32 v93, 1.0, v96
	v_mov_b32_e32 v89, v93
	v_rcp_f32_e32 v96, v88
	v_mul_f32_e32 v90, 0xbfb8aa3b, v90
	v_mul_f32_e32 v91, 0xbfb8aa3b, v91
	v_exp_f32_e32 v90, v90
	v_mul_f32_e32 v93, 1.0, v96
	v_mov_b32_e32 v88, v93
	v_mul_f32_e32 v93, 0xbfb8aa3b, v100
	v_exp_f32_e32 v93, v93
	v_pk_mul_f32 v[88:89], v[88:89], v[108:109]
	v_exp_f32_e32 v91, v91
	v_pk_add_f32 v[92:93], v[92:93], 1.0 op_sel_hi:[1,0]
	s_nop 0
	v_rcp_f32_e32 v108, v93
	v_pk_add_f32 v[90:91], v[90:91], 1.0 op_sel_hi:[1,0]
	v_mul_f32_e32 v96, v100, v108
	v_mov_b32_e32 v93, v96
	v_rcp_f32_e32 v100, v92
	s_nop 0
	v_mul_f32_e32 v96, v112, v100
	v_mov_b32_e32 v92, v96
	v_pk_mul_f32 v[88:89], v[92:93], v[88:89]
	v_and_b32_e32 v100, 0xffff0000, v233
	v_cvt_pk_bf16_f32 v88, v88, v89
	v_mul_f32_e32 v89, 0xbfb8aa3b, v94
	v_exp_f32_e32 v92, v89
	v_mul_f32_e32 v89, 0xbfb8aa3b, v95
	v_exp_f32_e32 v93, v89
	v_lshlrev_b32_e32 v89, 16, v233
	v_mul_f32_e32 v94, 0xbfb8aa3b, v89
	v_exp_f32_e32 v94, v94
	v_pk_add_f32 v[92:93], v[92:93], 1.0 op_sel_hi:[1,0]
	v_lshlrev_b32_e32 v96, 16, v229
	v_rcp_f32_e32 v101, v93
	v_and_b32_e32 v97, 0xffff0000, v229
	v_mul_f32_e32 v95, 1.0, v101
	v_mov_b32_e32 v93, v95
	v_rcp_f32_e32 v101, v92
	s_nop 0
	v_mul_f32_e32 v95, 1.0, v101
	v_mov_b32_e32 v92, v95
	v_mul_f32_e32 v95, 0xbfb8aa3b, v100
	v_exp_f32_e32 v95, v95
	v_pk_mul_f32 v[92:93], v[92:93], v[96:97]
	v_pk_add_f32 v[94:95], v[94:95], 1.0 op_sel_hi:[1,0]
	s_nop 0
	v_rcp_f32_e32 v97, v95
	s_nop 0
	v_mul_f32_e32 v96, v100, v97
	v_mov_b32_e32 v95, v96
	v_rcp_f32_e32 v97, v94
	s_nop 0
	v_mul_f32_e32 v96, v89, v97
	v_mov_b32_e32 v94, v96
	v_pk_mul_f32 v[92:93], v[94:95], v[92:93]
	v_lshlrev_b32_e32 v94, 16, v230
	v_cvt_pk_bf16_f32 v89, v92, v93
	v_and_b32_e32 v95, 0xffff0000, v230
	v_rcp_f32_e32 v98, v91
	v_lshlrev_b32_e32 v96, 16, v234
	v_and_b32_e32 v97, 0xffff0000, v234
	v_mul_f32_e32 v92, 0xbfb8aa3b, v96
	v_mul_f32_e32 v93, 1.0, v98
	v_mov_b32_e32 v91, v93
	v_rcp_f32_e32 v98, v90
	v_exp_f32_e32 v92, v92
	v_mul_f32_e32 v93, 1.0, v98
	v_mov_b32_e32 v90, v93
	v_mul_f32_e32 v93, 0xbfb8aa3b, v97
	v_exp_f32_e32 v93, v93
	v_pk_mul_f32 v[90:91], v[90:91], v[94:95]
	v_pk_add_f32 v[92:93], v[92:93], 1.0 op_sel_hi:[1,0]
	s_nop 0
	v_rcp_f32_e32 v95, v93
	s_nop 0
	v_mul_f32_e32 v94, v97, v95
	v_mov_b32_e32 v93, v94
	v_rcp_f32_e32 v95, v92
	s_nop 0
	v_mul_f32_e32 v94, v96, v95
	v_mov_b32_e32 v92, v94
	v_pk_mul_f32 v[90:91], v[92:93], v[90:91]
	v_lshlrev_b32_e32 v96, 16, v231
	v_cvt_pk_bf16_f32 v90, v90, v91
	v_mul_f32_e32 v91, 0xbfb8aa3b, v110
	v_exp_f32_e32 v92, v91
	v_mul_f32_e32 v91, 0xbfb8aa3b, v111
	v_exp_f32_e32 v93, v91
	v_and_b32_e32 v97, 0xffff0000, v231
	v_lshlrev_b32_e32 v91, 16, v235
	v_and_b32_e32 v98, 0xffff0000, v235
	v_pk_add_f32 v[92:93], v[92:93], 1.0 op_sel_hi:[1,0]
	v_mul_f32_e32 v94, 0xbfb8aa3b, v91
	v_rcp_f32_e32 v99, v93
	v_exp_f32_e32 v94, v94
	v_mul_f32_e32 v95, 1.0, v99
	v_mov_b32_e32 v93, v95
	v_rcp_f32_e32 v99, v92
	s_nop 0
	v_mul_f32_e32 v95, 1.0, v99
	v_mov_b32_e32 v92, v95
	v_mul_f32_e32 v95, 0xbfb8aa3b, v98
	v_exp_f32_e32 v95, v95
	v_pk_mul_f32 v[92:93], v[92:93], v[96:97]
	v_pk_add_f32 v[94:95], v[94:95], 1.0 op_sel_hi:[1,0]
	s_nop 0
	v_rcp_f32_e32 v97, v95
	s_nop 0
	v_mul_f32_e32 v96, v98, v97
	v_mov_b32_e32 v95, v96
	v_rcp_f32_e32 v97, v94
	s_nop 0
	v_mul_f32_e32 v96, v91, v97
	v_mov_b32_e32 v94, v96
	v_pk_mul_f32 v[92:93], v[94:95], v[92:93]
	s_nop 0
	v_cvt_pk_bf16_f32 v91, v92, v93
	global_store_dwordx4 v[214:215], v[88:91], off
	s_nop 1
	v_or_b32_e32 v248, 48, v154
	v_mad_i64_i32 v[248:249], s[0:1], v248, s14, v[144:145]
	v_lshl_add_u64 v[250:251], v[248:249], 0, v[146:147]
	v_add_co_u32_e32 v174, vcc, s15, v250
	s_nop 1
	v_addc_co_u32_e32 v175, vcc, 0, v251, vcc
	global_load_dwordx4 v[228:231], v[174:175], off
	global_load_dwordx4 v[232:235], v[250:251], off
	global_load_dwordx4 v[236:239], v[142:143], off offset:16
	global_load_dwordx4 v[240:243], v[142:143], off
	s_waitcnt vmcnt(5)
	v_pk_add_f32 v[100:101], v[84:85], v[208:209]
	v_pk_add_f32 v[84:85], v[82:83], v[186:187]
	v_pk_add_f32 v[82:83], v[80:81], v[184:185]
	v_mul_f32_e32 v80, 0xbfb8aa3b, v100
	v_mul_f32_e32 v81, 0xbfb8aa3b, v101
	v_exp_f32_e32 v80, v80
	v_exp_f32_e32 v81, v81
	v_lshlrev_b32_e32 v98, 16, v176
	v_and_b32_e32 v99, 0xffff0000, v176
	v_pk_add_f32 v[86:87], v[86:87], v[210:211]
	v_pk_add_f32 v[80:81], v[80:81], 1.0 op_sel_hi:[1,0]
	v_lshlrev_b32_e32 v100, 16, v180
	v_rcp_f32_e32 v97, v81
	v_and_b32_e32 v92, 0xffff0000, v180
	v_mul_f32_e32 v96, 0xbfb8aa3b, v100
	v_exp_f32_e32 v96, v96
	v_mul_f32_e32 v88, 1.0, v97
	v_mov_b32_e32 v81, v88
	v_rcp_f32_e32 v97, v80
	v_mul_f32_e32 v82, 0xbfb8aa3b, v82
	v_mul_f32_e32 v83, 0xbfb8aa3b, v83
	v_exp_f32_e32 v82, v82
	v_mul_f32_e32 v88, 1.0, v97
	v_mov_b32_e32 v80, v88
	v_mul_f32_e32 v88, 0xbfb8aa3b, v92
	v_exp_f32_e32 v97, v88
	v_pk_mul_f32 v[80:81], v[80:81], v[98:99]
	v_exp_f32_e32 v83, v83
	v_pk_add_f32 v[96:97], v[96:97], 1.0 op_sel_hi:[1,0]
	s_nop 0
	v_rcp_f32_e32 v98, v97
	v_pk_add_f32 v[82:83], v[82:83], 1.0 op_sel_hi:[1,0]
	v_mul_f32_e32 v88, v92, v98
	v_mov_b32_e32 v97, v88
	v_rcp_f32_e32 v92, v96
	s_nop 0
	v_mul_f32_e32 v88, v100, v92
	v_mov_b32_e32 v96, v88
	v_pk_mul_f32 v[80:81], v[96:97], v[80:81]
	v_and_b32_e32 v96, 0xffff0000, v181
	v_cvt_pk_bf16_f32 v80, v80, v81
	v_mul_f32_e32 v81, 0xbfb8aa3b, v86
	v_exp_f32_e32 v86, v81
	v_mul_f32_e32 v81, 0xbfb8aa3b, v87
	v_exp_f32_e32 v87, v81
	v_lshlrev_b32_e32 v81, 16, v181
	v_lshlrev_b32_e32 v92, 16, v177
	v_and_b32_e32 v93, 0xffff0000, v177
	v_pk_add_f32 v[86:87], v[86:87], 1.0 op_sel_hi:[1,0]
	v_mul_f32_e32 v88, 0xbfb8aa3b, v81
	v_rcp_f32_e32 v97, v87
	v_exp_f32_e32 v88, v88
	v_mul_f32_e32 v89, 1.0, v97
	v_mov_b32_e32 v87, v89
	v_rcp_f32_e32 v97, v86
	s_nop 0
	v_mul_f32_e32 v89, 1.0, v97
	v_mov_b32_e32 v86, v89
	v_mul_f32_e32 v89, 0xbfb8aa3b, v96
	v_exp_f32_e32 v89, v89
	v_pk_mul_f32 v[86:87], v[86:87], v[92:93]
	v_pk_add_f32 v[88:89], v[88:89], 1.0 op_sel_hi:[1,0]
	s_nop 0
	v_rcp_f32_e32 v93, v89
	s_nop 0
	v_mul_f32_e32 v92, v96, v93
	v_mov_b32_e32 v89, v92
	v_rcp_f32_e32 v93, v88
	s_nop 0
	v_mul_f32_e32 v92, v81, v93
	v_mov_b32_e32 v88, v92
	v_pk_mul_f32 v[86:87], v[88:89], v[86:87]
	v_lshlrev_b32_e32 v88, 16, v178
	v_cvt_pk_bf16_f32 v81, v86, v87
	v_and_b32_e32 v89, 0xffff0000, v178
	v_rcp_f32_e32 v90, v83
	v_lshlrev_b32_e32 v92, 16, v182
	v_and_b32_e32 v93, 0xffff0000, v182
	v_mul_f32_e32 v86, 0xbfb8aa3b, v92
	v_mul_f32_e32 v87, 1.0, v90
	v_mov_b32_e32 v83, v87
	v_rcp_f32_e32 v90, v82
	v_exp_f32_e32 v86, v86
	v_mul_f32_e32 v87, 1.0, v90
	v_mov_b32_e32 v82, v87
	v_mul_f32_e32 v87, 0xbfb8aa3b, v93
	v_exp_f32_e32 v87, v87
	v_pk_mul_f32 v[82:83], v[82:83], v[88:89]
	v_pk_add_f32 v[86:87], v[86:87], 1.0 op_sel_hi:[1,0]
	s_nop 0
	v_rcp_f32_e32 v89, v87
	s_nop 0
	v_mul_f32_e32 v88, v93, v89
	v_mov_b32_e32 v87, v88
	v_rcp_f32_e32 v89, v86
	s_nop 0
	v_mul_f32_e32 v88, v92, v89
	v_mov_b32_e32 v86, v88
	v_pk_mul_f32 v[82:83], v[86:87], v[82:83]
	v_lshlrev_b32_e32 v88, 16, v179
	v_cvt_pk_bf16_f32 v82, v82, v83
	v_mul_f32_e32 v83, 0xbfb8aa3b, v84
	v_exp_f32_e32 v84, v83
	v_mul_f32_e32 v83, 0xbfb8aa3b, v85
	v_exp_f32_e32 v85, v83
	v_and_b32_e32 v89, 0xffff0000, v179
	v_lshlrev_b32_e32 v83, 16, v183
	v_and_b32_e32 v90, 0xffff0000, v183
	v_pk_add_f32 v[84:85], v[84:85], 1.0 op_sel_hi:[1,0]
	v_mul_f32_e32 v86, 0xbfb8aa3b, v83
	v_rcp_f32_e32 v91, v85
	v_exp_f32_e32 v86, v86
	v_mul_f32_e32 v87, 1.0, v91
	v_mov_b32_e32 v85, v87
	v_rcp_f32_e32 v91, v84
	s_nop 0
	v_mul_f32_e32 v87, 1.0, v91
	v_mov_b32_e32 v84, v87
	v_mul_f32_e32 v87, 0xbfb8aa3b, v90
	v_exp_f32_e32 v87, v87
	v_pk_mul_f32 v[84:85], v[84:85], v[88:89]
	v_pk_add_f32 v[86:87], v[86:87], 1.0 op_sel_hi:[1,0]
	s_nop 0
	v_rcp_f32_e32 v89, v87
	s_nop 0
	v_mul_f32_e32 v88, v90, v89
	v_mov_b32_e32 v87, v88
	v_rcp_f32_e32 v89, v86
	s_nop 0
	v_mul_f32_e32 v88, v83, v89
	v_mov_b32_e32 v86, v88
	v_pk_mul_f32 v[84:85], v[86:87], v[84:85]
	s_nop 0
	v_cvt_pk_bf16_f32 v83, v84, v85
	global_store_dwordx4 v[214:215], v[80:83], off offset:256
	global_load_dwordx4 v[176:179], v[174:175], off offset:256
	global_load_dwordx4 v[180:183], v[250:251], off offset:256
	global_load_dwordx4 v[184:187], v[142:143], off offset:528
	global_load_dwordx4 v[208:211], v[142:143], off offset:512
	s_waitcnt vmcnt(5)
	v_pk_add_f32 v[94:95], v[74:75], v[238:239]
	v_pk_add_f32 v[76:77], v[76:77], v[240:241]
	v_pk_add_f32 v[74:75], v[72:73], v[236:237]
	v_mul_f32_e32 v72, 0xbfb8aa3b, v76
	v_mul_f32_e32 v73, 0xbfb8aa3b, v77
	v_exp_f32_e32 v72, v72
	v_exp_f32_e32 v73, v73
	v_lshlrev_b32_e32 v92, 16, v228
	v_and_b32_e32 v93, 0xffff0000, v228
	v_pk_add_f32 v[78:79], v[78:79], v[242:243]
	v_pk_add_f32 v[72:73], v[72:73], 1.0 op_sel_hi:[1,0]
	v_lshlrev_b32_e32 v96, 16, v232
	v_rcp_f32_e32 v80, v73
	v_and_b32_e32 v84, 0xffff0000, v232
	v_mul_f32_e32 v76, 0xbfb8aa3b, v96
	v_exp_f32_e32 v76, v76
	v_mul_f32_e32 v77, 1.0, v80
	v_mov_b32_e32 v73, v77
	v_rcp_f32_e32 v80, v72
	v_mul_f32_e32 v74, 0xbfb8aa3b, v74
	v_mul_f32_e32 v75, 0xbfb8aa3b, v75
	v_exp_f32_e32 v74, v74
	v_mul_f32_e32 v77, 1.0, v80
	v_mov_b32_e32 v72, v77
	v_mul_f32_e32 v77, 0xbfb8aa3b, v84
	v_exp_f32_e32 v77, v77
	v_pk_mul_f32 v[72:73], v[72:73], v[92:93]
	v_exp_f32_e32 v75, v75
	v_pk_add_f32 v[76:77], v[76:77], 1.0 op_sel_hi:[1,0]
	s_nop 0
	v_rcp_f32_e32 v92, v77
	v_pk_add_f32 v[74:75], v[74:75], 1.0 op_sel_hi:[1,0]
	v_mul_f32_e32 v80, v84, v92
	v_mov_b32_e32 v77, v80
	v_rcp_f32_e32 v84, v76
	s_nop 0
	v_mul_f32_e32 v80, v96, v84
	v_mov_b32_e32 v76, v80
	v_pk_mul_f32 v[72:73], v[76:77], v[72:73]
	v_and_b32_e32 v84, 0xffff0000, v233
	v_cvt_pk_bf16_f32 v72, v72, v73
	v_mul_f32_e32 v73, 0xbfb8aa3b, v78
	v_exp_f32_e32 v76, v73
	v_mul_f32_e32 v73, 0xbfb8aa3b, v79
	v_exp_f32_e32 v77, v73
	v_lshlrev_b32_e32 v73, 16, v233
	v_mul_f32_e32 v78, 0xbfb8aa3b, v73
	v_exp_f32_e32 v78, v78
	v_pk_add_f32 v[76:77], v[76:77], 1.0 op_sel_hi:[1,0]
	v_lshlrev_b32_e32 v80, 16, v229
	v_rcp_f32_e32 v85, v77
	v_and_b32_e32 v81, 0xffff0000, v229
	v_mul_f32_e32 v79, 1.0, v85
	v_mov_b32_e32 v77, v79
	v_rcp_f32_e32 v85, v76
	s_nop 0
	v_mul_f32_e32 v79, 1.0, v85
	v_mov_b32_e32 v76, v79
	v_mul_f32_e32 v79, 0xbfb8aa3b, v84
	v_exp_f32_e32 v79, v79
	v_pk_mul_f32 v[76:77], v[76:77], v[80:81]
	v_pk_add_f32 v[78:79], v[78:79], 1.0 op_sel_hi:[1,0]
	s_nop 0
	v_rcp_f32_e32 v81, v79
	s_nop 0
	v_mul_f32_e32 v80, v84, v81
	v_mov_b32_e32 v79, v80
	v_rcp_f32_e32 v81, v78
	s_nop 0
	v_mul_f32_e32 v80, v73, v81
	v_mov_b32_e32 v78, v80
	v_pk_mul_f32 v[76:77], v[78:79], v[76:77]
	v_lshlrev_b32_e32 v78, 16, v230
	v_cvt_pk_bf16_f32 v73, v76, v77
	v_and_b32_e32 v79, 0xffff0000, v230
	v_rcp_f32_e32 v82, v75
	v_lshlrev_b32_e32 v80, 16, v234
	v_and_b32_e32 v81, 0xffff0000, v234
	v_mul_f32_e32 v76, 0xbfb8aa3b, v80
	v_mul_f32_e32 v77, 1.0, v82
	v_mov_b32_e32 v75, v77
	v_rcp_f32_e32 v82, v74
	v_exp_f32_e32 v76, v76
	v_mul_f32_e32 v77, 1.0, v82
	v_mov_b32_e32 v74, v77
	v_mul_f32_e32 v77, 0xbfb8aa3b, v81
	v_exp_f32_e32 v77, v77
	v_pk_mul_f32 v[74:75], v[74:75], v[78:79]
	v_pk_add_f32 v[76:77], v[76:77], 1.0 op_sel_hi:[1,0]
	s_nop 0
	v_rcp_f32_e32 v79, v77
	s_nop 0
	v_mul_f32_e32 v78, v81, v79
	v_mov_b32_e32 v77, v78
	v_rcp_f32_e32 v79, v76
	s_nop 0
	v_mul_f32_e32 v78, v80, v79
	v_mov_b32_e32 v76, v78
	v_pk_mul_f32 v[74:75], v[76:77], v[74:75]
	v_lshlrev_b32_e32 v80, 16, v231
	v_cvt_pk_bf16_f32 v74, v74, v75
	v_mul_f32_e32 v75, 0xbfb8aa3b, v94
	v_exp_f32_e32 v76, v75
	v_mul_f32_e32 v75, 0xbfb8aa3b, v95
	v_exp_f32_e32 v77, v75
	v_and_b32_e32 v81, 0xffff0000, v231
	v_lshlrev_b32_e32 v75, 16, v235
	v_and_b32_e32 v82, 0xffff0000, v235
	v_pk_add_f32 v[76:77], v[76:77], 1.0 op_sel_hi:[1,0]
	v_mul_f32_e32 v78, 0xbfb8aa3b, v75
	v_rcp_f32_e32 v83, v77
	v_exp_f32_e32 v78, v78
	v_mul_f32_e32 v79, 1.0, v83
	v_mov_b32_e32 v77, v79
	v_rcp_f32_e32 v83, v76
	s_nop 0
	v_mul_f32_e32 v79, 1.0, v83
	v_mov_b32_e32 v76, v79
	v_mul_f32_e32 v79, 0xbfb8aa3b, v82
	v_exp_f32_e32 v79, v79
	v_pk_mul_f32 v[76:77], v[76:77], v[80:81]
	v_pk_add_f32 v[78:79], v[78:79], 1.0 op_sel_hi:[1,0]
	s_nop 0
	v_rcp_f32_e32 v81, v79
	s_nop 0
	v_mul_f32_e32 v80, v82, v81
	v_mov_b32_e32 v79, v80
	v_rcp_f32_e32 v81, v78
	s_nop 0
	v_mul_f32_e32 v80, v75, v81
	v_mov_b32_e32 v78, v80
	v_pk_mul_f32 v[76:77], v[78:79], v[76:77]
	s_nop 0
	v_cvt_pk_bf16_f32 v75, v76, v77
	global_store_dwordx4 v[250:251], v[72:75], off
	s_nop 1
	v_add_u32_e32 v212, 0x80, v154
	v_mad_i64_i32 v[212:213], s[0:1], v212, s14, v[144:145]
	v_lshl_add_u64 v[214:215], v[212:213], 0, v[146:147]
	v_add_co_u32_e32 v246, vcc, s15, v214
	s_nop 1
	v_addc_co_u32_e32 v247, vcc, 0, v215, vcc
	global_load_dwordx4 v[228:231], v[246:247], off
	global_load_dwordx4 v[232:235], v[214:215], off
	global_load_dwordx4 v[236:239], v[142:143], off offset:16
	global_load_dwordx4 v[240:243], v[142:143], off
	s_waitcnt vmcnt(5)
	v_pk_add_f32 v[84:85], v[68:69], v[208:209]
	v_pk_add_f32 v[68:69], v[66:67], v[186:187]
	v_pk_add_f32 v[66:67], v[64:65], v[184:185]
	v_mul_f32_e32 v64, 0xbfb8aa3b, v84
	v_mul_f32_e32 v65, 0xbfb8aa3b, v85
	v_exp_f32_e32 v64, v64
	v_exp_f32_e32 v65, v65
	v_lshlrev_b32_e32 v82, 16, v176
	v_and_b32_e32 v83, 0xffff0000, v176
	v_pk_add_f32 v[70:71], v[70:71], v[210:211]
	v_pk_add_f32 v[64:65], v[64:65], 1.0 op_sel_hi:[1,0]
	v_lshlrev_b32_e32 v84, 16, v180
	v_rcp_f32_e32 v81, v65
	v_and_b32_e32 v76, 0xffff0000, v180
	v_mul_f32_e32 v80, 0xbfb8aa3b, v84
	v_exp_f32_e32 v80, v80
	v_mul_f32_e32 v72, 1.0, v81
	v_mov_b32_e32 v65, v72
	v_rcp_f32_e32 v81, v64
	v_mul_f32_e32 v66, 0xbfb8aa3b, v66
	v_mul_f32_e32 v67, 0xbfb8aa3b, v67
	v_exp_f32_e32 v66, v66
	v_mul_f32_e32 v72, 1.0, v81
	v_mov_b32_e32 v64, v72
	v_mul_f32_e32 v72, 0xbfb8aa3b, v76
	v_exp_f32_e32 v81, v72
	v_pk_mul_f32 v[64:65], v[64:65], v[82:83]
	v_exp_f32_e32 v67, v67
	v_pk_add_f32 v[80:81], v[80:81], 1.0 op_sel_hi:[1,0]
	s_nop 0
	v_rcp_f32_e32 v82, v81
	v_pk_add_f32 v[66:67], v[66:67], 1.0 op_sel_hi:[1,0]
	v_mul_f32_e32 v72, v76, v82
	v_mov_b32_e32 v81, v72
	v_rcp_f32_e32 v76, v80
	s_nop 0
	v_mul_f32_e32 v72, v84, v76
	v_mov_b32_e32 v80, v72
	v_pk_mul_f32 v[64:65], v[80:81], v[64:65]
	v_and_b32_e32 v80, 0xffff0000, v181
	v_cvt_pk_bf16_f32 v64, v64, v65
	v_mul_f32_e32 v65, 0xbfb8aa3b, v70
	v_exp_f32_e32 v70, v65
	v_mul_f32_e32 v65, 0xbfb8aa3b, v71
	v_exp_f32_e32 v71, v65
	v_lshlrev_b32_e32 v65, 16, v181
	v_lshlrev_b32_e32 v76, 16, v177
	v_and_b32_e32 v77, 0xffff0000, v177
	v_pk_add_f32 v[70:71], v[70:71], 1.0 op_sel_hi:[1,0]
	v_mul_f32_e32 v72, 0xbfb8aa3b, v65
	v_rcp_f32_e32 v81, v71
	v_exp_f32_e32 v72, v72
	v_mul_f32_e32 v73, 1.0, v81
	v_mov_b32_e32 v71, v73
	v_rcp_f32_e32 v81, v70
	s_nop 0
	v_mul_f32_e32 v73, 1.0, v81
	v_mov_b32_e32 v70, v73
	v_mul_f32_e32 v73, 0xbfb8aa3b, v80
	v_exp_f32_e32 v73, v73
	v_pk_mul_f32 v[70:71], v[70:71], v[76:77]
	v_pk_add_f32 v[72:73], v[72:73], 1.0 op_sel_hi:[1,0]
	s_nop 0
	v_rcp_f32_e32 v77, v73
	s_nop 0
	v_mul_f32_e32 v76, v80, v77
	v_mov_b32_e32 v73, v76
	v_rcp_f32_e32 v77, v72
	s_nop 0
	v_mul_f32_e32 v76, v65, v77
	v_mov_b32_e32 v72, v76
	v_pk_mul_f32 v[70:71], v[72:73], v[70:71]
	v_lshlrev_b32_e32 v72, 16, v178
	v_cvt_pk_bf16_f32 v65, v70, v71
	v_and_b32_e32 v73, 0xffff0000, v178
	v_rcp_f32_e32 v74, v67
	v_lshlrev_b32_e32 v76, 16, v182
	v_and_b32_e32 v77, 0xffff0000, v182
	v_mul_f32_e32 v70, 0xbfb8aa3b, v76
	v_mul_f32_e32 v71, 1.0, v74
	v_mov_b32_e32 v67, v71
	v_rcp_f32_e32 v74, v66
	v_exp_f32_e32 v70, v70
	v_mul_f32_e32 v71, 1.0, v74
	v_mov_b32_e32 v66, v71
	v_mul_f32_e32 v71, 0xbfb8aa3b, v77
	v_exp_f32_e32 v71, v71
	v_pk_mul_f32 v[66:67], v[66:67], v[72:73]
	v_pk_add_f32 v[70:71], v[70:71], 1.0 op_sel_hi:[1,0]
	s_nop 0
	v_rcp_f32_e32 v73, v71
	s_nop 0
	v_mul_f32_e32 v72, v77, v73
	v_mov_b32_e32 v71, v72
	v_rcp_f32_e32 v73, v70
	s_nop 0
	v_mul_f32_e32 v72, v76, v73
	v_mov_b32_e32 v70, v72
	v_pk_mul_f32 v[66:67], v[70:71], v[66:67]
	v_lshlrev_b32_e32 v72, 16, v179
	v_cvt_pk_bf16_f32 v66, v66, v67
	v_mul_f32_e32 v67, 0xbfb8aa3b, v68
	v_exp_f32_e32 v68, v67
	v_mul_f32_e32 v67, 0xbfb8aa3b, v69
	v_exp_f32_e32 v69, v67
	v_and_b32_e32 v73, 0xffff0000, v179
	v_lshlrev_b32_e32 v67, 16, v183
	v_and_b32_e32 v74, 0xffff0000, v183
	v_pk_add_f32 v[68:69], v[68:69], 1.0 op_sel_hi:[1,0]
	v_mul_f32_e32 v70, 0xbfb8aa3b, v67
	v_rcp_f32_e32 v75, v69
	v_exp_f32_e32 v70, v70
	v_mul_f32_e32 v71, 1.0, v75
	v_mov_b32_e32 v69, v71
	v_rcp_f32_e32 v75, v68
	s_nop 0
	v_mul_f32_e32 v71, 1.0, v75
	v_mov_b32_e32 v68, v71
	v_mul_f32_e32 v71, 0xbfb8aa3b, v74
	v_exp_f32_e32 v71, v71
	v_pk_mul_f32 v[68:69], v[68:69], v[72:73]
	v_pk_add_f32 v[70:71], v[70:71], 1.0 op_sel_hi:[1,0]
	s_nop 0
	v_rcp_f32_e32 v73, v71
	s_nop 0
	v_mul_f32_e32 v72, v74, v73
	v_mov_b32_e32 v71, v72
	v_rcp_f32_e32 v73, v70
	s_nop 0
	v_mul_f32_e32 v72, v67, v73
	v_mov_b32_e32 v70, v72
	v_pk_mul_f32 v[68:69], v[70:71], v[68:69]
	s_nop 0
	v_cvt_pk_bf16_f32 v67, v68, v69
	global_store_dwordx4 v[250:251], v[64:67], off offset:256
	global_load_dwordx4 v[176:179], v[246:247], off offset:256
	global_load_dwordx4 v[180:183], v[214:215], off offset:256
	global_load_dwordx4 v[184:187], v[142:143], off offset:528
	global_load_dwordx4 v[208:211], v[142:143], off offset:512
	s_waitcnt vmcnt(5)
	v_pk_add_f32 v[78:79], v[58:59], v[238:239]
	v_pk_add_f32 v[60:61], v[60:61], v[240:241]
	v_pk_add_f32 v[58:59], v[56:57], v[236:237]
	v_mul_f32_e32 v56, 0xbfb8aa3b, v60
	v_mul_f32_e32 v57, 0xbfb8aa3b, v61
	v_exp_f32_e32 v56, v56
	v_exp_f32_e32 v57, v57
	v_lshlrev_b32_e32 v76, 16, v228
	v_and_b32_e32 v77, 0xffff0000, v228
	v_pk_add_f32 v[62:63], v[62:63], v[242:243]
	v_pk_add_f32 v[56:57], v[56:57], 1.0 op_sel_hi:[1,0]
	v_lshlrev_b32_e32 v80, 16, v232
	v_rcp_f32_e32 v64, v57
	v_and_b32_e32 v68, 0xffff0000, v232
	v_mul_f32_e32 v60, 0xbfb8aa3b, v80
	v_exp_f32_e32 v60, v60
	v_mul_f32_e32 v61, 1.0, v64
	v_mov_b32_e32 v57, v61
	v_rcp_f32_e32 v64, v56
	v_mul_f32_e32 v58, 0xbfb8aa3b, v58
	v_mul_f32_e32 v59, 0xbfb8aa3b, v59
	v_exp_f32_e32 v58, v58
	v_mul_f32_e32 v61, 1.0, v64
	v_mov_b32_e32 v56, v61
	v_mul_f32_e32 v61, 0xbfb8aa3b, v68
	v_exp_f32_e32 v61, v61
	v_pk_mul_f32 v[56:57], v[56:57], v[76:77]
	v_exp_f32_e32 v59, v59
	v_pk_add_f32 v[60:61], v[60:61], 1.0 op_sel_hi:[1,0]
	s_nop 0
	v_rcp_f32_e32 v76, v61
	v_pk_add_f32 v[58:59], v[58:59], 1.0 op_sel_hi:[1,0]
	v_mul_f32_e32 v64, v68, v76
	v_mov_b32_e32 v61, v64
	v_rcp_f32_e32 v68, v60
	s_nop 0
	v_mul_f32_e32 v64, v80, v68
	v_mov_b32_e32 v60, v64
	v_pk_mul_f32 v[56:57], v[60:61], v[56:57]
	v_and_b32_e32 v68, 0xffff0000, v233
	v_cvt_pk_bf16_f32 v56, v56, v57
	v_mul_f32_e32 v57, 0xbfb8aa3b, v62
	v_exp_f32_e32 v60, v57
	v_mul_f32_e32 v57, 0xbfb8aa3b, v63
	v_exp_f32_e32 v61, v57
	v_lshlrev_b32_e32 v57, 16, v233
	v_mul_f32_e32 v62, 0xbfb8aa3b, v57
	v_exp_f32_e32 v62, v62
	v_pk_add_f32 v[60:61], v[60:61], 1.0 op_sel_hi:[1,0]
	v_lshlrev_b32_e32 v64, 16, v229
	v_rcp_f32_e32 v69, v61
	v_and_b32_e32 v65, 0xffff0000, v229
	v_mul_f32_e32 v63, 1.0, v69
	v_mov_b32_e32 v61, v63
	v_rcp_f32_e32 v69, v60
	s_nop 0
	v_mul_f32_e32 v63, 1.0, v69
	v_mov_b32_e32 v60, v63
	v_mul_f32_e32 v63, 0xbfb8aa3b, v68
	v_exp_f32_e32 v63, v63
	v_pk_mul_f32 v[60:61], v[60:61], v[64:65]
	v_pk_add_f32 v[62:63], v[62:63], 1.0 op_sel_hi:[1,0]
	s_nop 0
	v_rcp_f32_e32 v65, v63
	s_nop 0
	v_mul_f32_e32 v64, v68, v65
	v_mov_b32_e32 v63, v64
	v_rcp_f32_e32 v65, v62
	s_nop 0
	v_mul_f32_e32 v64, v57, v65
	v_mov_b32_e32 v62, v64
	v_pk_mul_f32 v[60:61], v[62:63], v[60:61]
	v_lshlrev_b32_e32 v62, 16, v230
	v_cvt_pk_bf16_f32 v57, v60, v61
	v_and_b32_e32 v63, 0xffff0000, v230
	v_rcp_f32_e32 v66, v59
	v_lshlrev_b32_e32 v64, 16, v234
	v_and_b32_e32 v65, 0xffff0000, v234
	v_mul_f32_e32 v60, 0xbfb8aa3b, v64
	v_mul_f32_e32 v61, 1.0, v66
	v_mov_b32_e32 v59, v61
	v_rcp_f32_e32 v66, v58
	v_exp_f32_e32 v60, v60
	v_mul_f32_e32 v61, 1.0, v66
	v_mov_b32_e32 v58, v61
	v_mul_f32_e32 v61, 0xbfb8aa3b, v65
	v_exp_f32_e32 v61, v61
	v_pk_mul_f32 v[58:59], v[58:59], v[62:63]
	v_pk_add_f32 v[60:61], v[60:61], 1.0 op_sel_hi:[1,0]
	s_nop 0
	v_rcp_f32_e32 v63, v61
	s_nop 0
	v_mul_f32_e32 v62, v65, v63
	v_mov_b32_e32 v61, v62
	v_rcp_f32_e32 v63, v60
	s_nop 0
	v_mul_f32_e32 v62, v64, v63
	v_mov_b32_e32 v60, v62
	v_pk_mul_f32 v[58:59], v[60:61], v[58:59]
	v_lshlrev_b32_e32 v64, 16, v231
	v_cvt_pk_bf16_f32 v58, v58, v59
	v_mul_f32_e32 v59, 0xbfb8aa3b, v78
	v_exp_f32_e32 v60, v59
	v_mul_f32_e32 v59, 0xbfb8aa3b, v79
	v_exp_f32_e32 v61, v59
	v_and_b32_e32 v65, 0xffff0000, v231
	v_lshlrev_b32_e32 v59, 16, v235
	v_and_b32_e32 v66, 0xffff0000, v235
	v_pk_add_f32 v[60:61], v[60:61], 1.0 op_sel_hi:[1,0]
	v_mul_f32_e32 v62, 0xbfb8aa3b, v59
	v_rcp_f32_e32 v67, v61
	v_exp_f32_e32 v62, v62
	v_mul_f32_e32 v63, 1.0, v67
	v_mov_b32_e32 v61, v63
	v_rcp_f32_e32 v67, v60
	s_nop 0
	v_mul_f32_e32 v63, 1.0, v67
	v_mov_b32_e32 v60, v63
	v_mul_f32_e32 v63, 0xbfb8aa3b, v66
	v_exp_f32_e32 v63, v63
	v_pk_mul_f32 v[60:61], v[60:61], v[64:65]
	v_pk_add_f32 v[62:63], v[62:63], 1.0 op_sel_hi:[1,0]
	s_nop 0
	v_rcp_f32_e32 v65, v63
	s_nop 0
	v_mul_f32_e32 v64, v66, v65
	v_mov_b32_e32 v63, v64
	v_rcp_f32_e32 v65, v62
	s_nop 0
	v_mul_f32_e32 v64, v59, v65
	v_mov_b32_e32 v62, v64
	v_pk_mul_f32 v[60:61], v[62:63], v[60:61]
	s_nop 0
	v_cvt_pk_bf16_f32 v59, v60, v61
	global_store_dwordx4 v[214:215], v[56:59], off
	s_nop 1
	v_add_u32_e32 v248, 0x90, v154
	v_mad_i64_i32 v[248:249], s[0:1], v248, s14, v[144:145]
	v_lshl_add_u64 v[250:251], v[248:249], 0, v[146:147]
	v_add_co_u32_e32 v174, vcc, s15, v250
	s_nop 1
	v_addc_co_u32_e32 v175, vcc, 0, v251, vcc
	global_load_dwordx4 v[228:231], v[174:175], off
	global_load_dwordx4 v[232:235], v[250:251], off
	global_load_dwordx4 v[236:239], v[142:143], off offset:16
	global_load_dwordx4 v[240:243], v[142:143], off
	s_waitcnt vmcnt(5)
	v_pk_add_f32 v[68:69], v[52:53], v[208:209]
	v_pk_add_f32 v[52:53], v[50:51], v[186:187]
	v_pk_add_f32 v[50:51], v[48:49], v[184:185]
	v_mul_f32_e32 v48, 0xbfb8aa3b, v68
	v_mul_f32_e32 v49, 0xbfb8aa3b, v69
	v_exp_f32_e32 v48, v48
	v_exp_f32_e32 v49, v49
	v_lshlrev_b32_e32 v66, 16, v176
	v_and_b32_e32 v67, 0xffff0000, v176
	v_pk_add_f32 v[54:55], v[54:55], v[210:211]
	v_pk_add_f32 v[48:49], v[48:49], 1.0 op_sel_hi:[1,0]
	v_lshlrev_b32_e32 v68, 16, v180
	v_rcp_f32_e32 v65, v49
	v_and_b32_e32 v60, 0xffff0000, v180
	v_mul_f32_e32 v64, 0xbfb8aa3b, v68
	v_exp_f32_e32 v64, v64
	v_mul_f32_e32 v56, 1.0, v65
	v_mov_b32_e32 v49, v56
	v_rcp_f32_e32 v65, v48
	v_mul_f32_e32 v50, 0xbfb8aa3b, v50
	v_mul_f32_e32 v51, 0xbfb8aa3b, v51
	v_exp_f32_e32 v50, v50
	v_mul_f32_e32 v56, 1.0, v65
	v_mov_b32_e32 v48, v56
	v_mul_f32_e32 v56, 0xbfb8aa3b, v60
	v_exp_f32_e32 v65, v56
	v_pk_mul_f32 v[48:49], v[48:49], v[66:67]
	v_exp_f32_e32 v51, v51
	v_pk_add_f32 v[64:65], v[64:65], 1.0 op_sel_hi:[1,0]
	s_nop 0
	v_rcp_f32_e32 v66, v65
	v_pk_add_f32 v[50:51], v[50:51], 1.0 op_sel_hi:[1,0]
	v_mul_f32_e32 v56, v60, v66
	v_mov_b32_e32 v65, v56
	v_rcp_f32_e32 v60, v64
	s_nop 0
	v_mul_f32_e32 v56, v68, v60
	v_mov_b32_e32 v64, v56
	v_pk_mul_f32 v[48:49], v[64:65], v[48:49]
	v_and_b32_e32 v64, 0xffff0000, v181
	v_cvt_pk_bf16_f32 v48, v48, v49
	v_mul_f32_e32 v49, 0xbfb8aa3b, v54
	v_exp_f32_e32 v54, v49
	v_mul_f32_e32 v49, 0xbfb8aa3b, v55
	v_exp_f32_e32 v55, v49
	v_lshlrev_b32_e32 v49, 16, v181
	v_lshlrev_b32_e32 v60, 16, v177
	v_and_b32_e32 v61, 0xffff0000, v177
	v_pk_add_f32 v[54:55], v[54:55], 1.0 op_sel_hi:[1,0]
	v_mul_f32_e32 v56, 0xbfb8aa3b, v49
	v_rcp_f32_e32 v65, v55
	v_exp_f32_e32 v56, v56
	v_mul_f32_e32 v57, 1.0, v65
	v_mov_b32_e32 v55, v57
	v_rcp_f32_e32 v65, v54
	s_nop 0
	v_mul_f32_e32 v57, 1.0, v65
	v_mov_b32_e32 v54, v57
	v_mul_f32_e32 v57, 0xbfb8aa3b, v64
	v_exp_f32_e32 v57, v57
	v_pk_mul_f32 v[54:55], v[54:55], v[60:61]
	v_pk_add_f32 v[56:57], v[56:57], 1.0 op_sel_hi:[1,0]
	s_nop 0
	v_rcp_f32_e32 v61, v57
	s_nop 0
	v_mul_f32_e32 v60, v64, v61
	v_mov_b32_e32 v57, v60
	v_rcp_f32_e32 v61, v56
	s_nop 0
	v_mul_f32_e32 v60, v49, v61
	v_mov_b32_e32 v56, v60
	v_pk_mul_f32 v[54:55], v[56:57], v[54:55]
	v_lshlrev_b32_e32 v56, 16, v178
	v_cvt_pk_bf16_f32 v49, v54, v55
	v_and_b32_e32 v57, 0xffff0000, v178
	v_rcp_f32_e32 v58, v51
	v_lshlrev_b32_e32 v60, 16, v182
	v_and_b32_e32 v61, 0xffff0000, v182
	v_mul_f32_e32 v54, 0xbfb8aa3b, v60
	v_mul_f32_e32 v55, 1.0, v58
	v_mov_b32_e32 v51, v55
	v_rcp_f32_e32 v58, v50
	v_exp_f32_e32 v54, v54
	v_mul_f32_e32 v55, 1.0, v58
	v_mov_b32_e32 v50, v55
	v_mul_f32_e32 v55, 0xbfb8aa3b, v61
	v_exp_f32_e32 v55, v55
	v_pk_mul_f32 v[50:51], v[50:51], v[56:57]
	v_pk_add_f32 v[54:55], v[54:55], 1.0 op_sel_hi:[1,0]
	s_nop 0
	v_rcp_f32_e32 v57, v55
	s_nop 0
	v_mul_f32_e32 v56, v61, v57
	v_mov_b32_e32 v55, v56
	v_rcp_f32_e32 v57, v54
	s_nop 0
	v_mul_f32_e32 v56, v60, v57
	v_mov_b32_e32 v54, v56
	v_pk_mul_f32 v[50:51], v[54:55], v[50:51]
	v_lshlrev_b32_e32 v56, 16, v179
	v_cvt_pk_bf16_f32 v50, v50, v51
	v_mul_f32_e32 v51, 0xbfb8aa3b, v52
	v_exp_f32_e32 v52, v51
	v_mul_f32_e32 v51, 0xbfb8aa3b, v53
	v_exp_f32_e32 v53, v51
	v_and_b32_e32 v57, 0xffff0000, v179
	v_lshlrev_b32_e32 v51, 16, v183
	v_and_b32_e32 v58, 0xffff0000, v183
	v_pk_add_f32 v[52:53], v[52:53], 1.0 op_sel_hi:[1,0]
	v_mul_f32_e32 v54, 0xbfb8aa3b, v51
	v_rcp_f32_e32 v59, v53
	v_exp_f32_e32 v54, v54
	v_mul_f32_e32 v55, 1.0, v59
	v_mov_b32_e32 v53, v55
	v_rcp_f32_e32 v59, v52
	s_nop 0
	v_mul_f32_e32 v55, 1.0, v59
	v_mov_b32_e32 v52, v55
	v_mul_f32_e32 v55, 0xbfb8aa3b, v58
	v_exp_f32_e32 v55, v55
	v_pk_mul_f32 v[52:53], v[52:53], v[56:57]
	v_pk_add_f32 v[54:55], v[54:55], 1.0 op_sel_hi:[1,0]
	s_nop 0
	v_rcp_f32_e32 v57, v55
	s_nop 0
	v_mul_f32_e32 v56, v58, v57
	v_mov_b32_e32 v55, v56
	v_rcp_f32_e32 v57, v54
	s_nop 0
	v_mul_f32_e32 v56, v51, v57
	v_mov_b32_e32 v54, v56
	v_pk_mul_f32 v[52:53], v[54:55], v[52:53]
	s_nop 0
	v_cvt_pk_bf16_f32 v51, v52, v53
	global_store_dwordx4 v[214:215], v[48:51], off offset:256
	global_load_dwordx4 v[176:179], v[174:175], off offset:256
	global_load_dwordx4 v[180:183], v[250:251], off offset:256
	global_load_dwordx4 v[184:187], v[142:143], off offset:528
	global_load_dwordx4 v[208:211], v[142:143], off offset:512
	s_waitcnt vmcnt(5)
	v_pk_add_f32 v[62:63], v[42:43], v[238:239]
	v_pk_add_f32 v[44:45], v[44:45], v[240:241]
	v_pk_add_f32 v[42:43], v[40:41], v[236:237]
	v_mul_f32_e32 v40, 0xbfb8aa3b, v44
	v_mul_f32_e32 v41, 0xbfb8aa3b, v45
	v_exp_f32_e32 v40, v40
	v_exp_f32_e32 v41, v41
	v_lshlrev_b32_e32 v60, 16, v228
	v_and_b32_e32 v61, 0xffff0000, v228
	v_pk_add_f32 v[46:47], v[46:47], v[242:243]
	v_pk_add_f32 v[40:41], v[40:41], 1.0 op_sel_hi:[1,0]
	v_lshlrev_b32_e32 v64, 16, v232
	v_rcp_f32_e32 v48, v41
	v_and_b32_e32 v52, 0xffff0000, v232
	v_mul_f32_e32 v44, 0xbfb8aa3b, v64
	v_exp_f32_e32 v44, v44
	v_mul_f32_e32 v45, 1.0, v48
	v_mov_b32_e32 v41, v45
	v_rcp_f32_e32 v48, v40
	v_mul_f32_e32 v42, 0xbfb8aa3b, v42
	v_mul_f32_e32 v43, 0xbfb8aa3b, v43
	v_exp_f32_e32 v42, v42
	v_mul_f32_e32 v45, 1.0, v48
	v_mov_b32_e32 v40, v45
	v_mul_f32_e32 v45, 0xbfb8aa3b, v52
	v_exp_f32_e32 v45, v45
	v_pk_mul_f32 v[40:41], v[40:41], v[60:61]
	v_exp_f32_e32 v43, v43
	v_pk_add_f32 v[44:45], v[44:45], 1.0 op_sel_hi:[1,0]
	s_nop 0
	v_rcp_f32_e32 v60, v45
	v_pk_add_f32 v[42:43], v[42:43], 1.0 op_sel_hi:[1,0]
	v_mul_f32_e32 v48, v52, v60
	v_mov_b32_e32 v45, v48
	v_rcp_f32_e32 v52, v44
	s_nop 0
	v_mul_f32_e32 v48, v64, v52
	v_mov_b32_e32 v44, v48
	v_pk_mul_f32 v[40:41], v[44:45], v[40:41]
	v_and_b32_e32 v52, 0xffff0000, v233
	v_cvt_pk_bf16_f32 v40, v40, v41
	v_mul_f32_e32 v41, 0xbfb8aa3b, v46
	v_exp_f32_e32 v44, v41
	v_mul_f32_e32 v41, 0xbfb8aa3b, v47
	v_exp_f32_e32 v45, v41
	v_lshlrev_b32_e32 v41, 16, v233
	v_mul_f32_e32 v46, 0xbfb8aa3b, v41
	v_exp_f32_e32 v46, v46
	v_pk_add_f32 v[44:45], v[44:45], 1.0 op_sel_hi:[1,0]
	v_lshlrev_b32_e32 v48, 16, v229
	v_rcp_f32_e32 v53, v45
	v_and_b32_e32 v49, 0xffff0000, v229
	v_mul_f32_e32 v47, 1.0, v53
	v_mov_b32_e32 v45, v47
	v_rcp_f32_e32 v53, v44
	s_nop 0
	v_mul_f32_e32 v47, 1.0, v53
	v_mov_b32_e32 v44, v47
	v_mul_f32_e32 v47, 0xbfb8aa3b, v52
	v_exp_f32_e32 v47, v47
	v_pk_mul_f32 v[44:45], v[44:45], v[48:49]
	v_pk_add_f32 v[46:47], v[46:47], 1.0 op_sel_hi:[1,0]
	s_nop 0
	v_rcp_f32_e32 v49, v47
	s_nop 0
	v_mul_f32_e32 v48, v52, v49
	v_mov_b32_e32 v47, v48
	v_rcp_f32_e32 v49, v46
	s_nop 0
	v_mul_f32_e32 v48, v41, v49
	v_mov_b32_e32 v46, v48
	v_pk_mul_f32 v[44:45], v[46:47], v[44:45]
	v_lshlrev_b32_e32 v46, 16, v230
	v_cvt_pk_bf16_f32 v41, v44, v45
	v_and_b32_e32 v47, 0xffff0000, v230
	v_rcp_f32_e32 v50, v43
	v_lshlrev_b32_e32 v48, 16, v234
	v_and_b32_e32 v49, 0xffff0000, v234
	v_mul_f32_e32 v44, 0xbfb8aa3b, v48
	v_mul_f32_e32 v45, 1.0, v50
	v_mov_b32_e32 v43, v45
	v_rcp_f32_e32 v50, v42
	v_exp_f32_e32 v44, v44
	v_mul_f32_e32 v45, 1.0, v50
	v_mov_b32_e32 v42, v45
	v_mul_f32_e32 v45, 0xbfb8aa3b, v49
	v_exp_f32_e32 v45, v45
	v_pk_mul_f32 v[42:43], v[42:43], v[46:47]
	v_pk_add_f32 v[44:45], v[44:45], 1.0 op_sel_hi:[1,0]
	s_nop 0
	v_rcp_f32_e32 v47, v45
	s_nop 0
	v_mul_f32_e32 v46, v49, v47
	v_mov_b32_e32 v45, v46
	v_rcp_f32_e32 v47, v44
	s_nop 0
	v_mul_f32_e32 v46, v48, v47
	v_mov_b32_e32 v44, v46
	v_pk_mul_f32 v[42:43], v[44:45], v[42:43]
	v_lshlrev_b32_e32 v48, 16, v231
	v_cvt_pk_bf16_f32 v42, v42, v43
	v_mul_f32_e32 v43, 0xbfb8aa3b, v62
	v_exp_f32_e32 v44, v43
	v_mul_f32_e32 v43, 0xbfb8aa3b, v63
	v_exp_f32_e32 v45, v43
	v_and_b32_e32 v49, 0xffff0000, v231
	v_lshlrev_b32_e32 v43, 16, v235
	v_and_b32_e32 v50, 0xffff0000, v235
	v_pk_add_f32 v[44:45], v[44:45], 1.0 op_sel_hi:[1,0]
	v_mul_f32_e32 v46, 0xbfb8aa3b, v43
	v_rcp_f32_e32 v51, v45
	v_exp_f32_e32 v46, v46
	v_mul_f32_e32 v47, 1.0, v51
	v_mov_b32_e32 v45, v47
	v_rcp_f32_e32 v51, v44
	s_nop 0
	v_mul_f32_e32 v47, 1.0, v51
	v_mov_b32_e32 v44, v47
	v_mul_f32_e32 v47, 0xbfb8aa3b, v50
	v_exp_f32_e32 v47, v47
	v_pk_mul_f32 v[44:45], v[44:45], v[48:49]
	v_pk_add_f32 v[46:47], v[46:47], 1.0 op_sel_hi:[1,0]
	s_nop 0
	v_rcp_f32_e32 v49, v47
	s_nop 0
	v_mul_f32_e32 v48, v50, v49
	v_mov_b32_e32 v47, v48
	v_rcp_f32_e32 v49, v46
	s_nop 0
	v_mul_f32_e32 v48, v43, v49
	v_mov_b32_e32 v46, v48
	v_pk_mul_f32 v[44:45], v[46:47], v[44:45]
	s_nop 0
	v_cvt_pk_bf16_f32 v43, v44, v45
	global_store_dwordx4 v[250:251], v[40:43], off
	s_nop 1
	v_add_u32_e32 v212, 0xa0, v154
	v_mad_i64_i32 v[212:213], s[0:1], v212, s14, v[144:145]
	v_lshl_add_u64 v[214:215], v[212:213], 0, v[146:147]
	v_add_co_u32_e32 v246, vcc, s15, v214
	s_nop 1
	v_addc_co_u32_e32 v247, vcc, 0, v215, vcc
	global_load_dwordx4 v[228:231], v[246:247], off
	global_load_dwordx4 v[232:235], v[214:215], off
	global_load_dwordx4 v[236:239], v[142:143], off offset:16
	global_load_dwordx4 v[240:243], v[142:143], off
	s_waitcnt vmcnt(5)
	v_pk_add_f32 v[52:53], v[36:37], v[208:209]
	v_pk_add_f32 v[36:37], v[34:35], v[186:187]
	v_pk_add_f32 v[34:35], v[32:33], v[184:185]
	v_mul_f32_e32 v32, 0xbfb8aa3b, v52
	v_mul_f32_e32 v33, 0xbfb8aa3b, v53
	v_exp_f32_e32 v32, v32
	v_exp_f32_e32 v33, v33
	v_lshlrev_b32_e32 v50, 16, v176
	v_and_b32_e32 v51, 0xffff0000, v176
	v_pk_add_f32 v[38:39], v[38:39], v[210:211]
	v_pk_add_f32 v[32:33], v[32:33], 1.0 op_sel_hi:[1,0]
	v_lshlrev_b32_e32 v52, 16, v180
	v_rcp_f32_e32 v49, v33
	v_and_b32_e32 v44, 0xffff0000, v180
	v_mul_f32_e32 v48, 0xbfb8aa3b, v52
	v_exp_f32_e32 v48, v48
	v_mul_f32_e32 v40, 1.0, v49
	v_mov_b32_e32 v33, v40
	v_rcp_f32_e32 v49, v32
	v_mul_f32_e32 v34, 0xbfb8aa3b, v34
	v_mul_f32_e32 v35, 0xbfb8aa3b, v35
	v_exp_f32_e32 v34, v34
	v_mul_f32_e32 v40, 1.0, v49
	v_mov_b32_e32 v32, v40
	v_mul_f32_e32 v40, 0xbfb8aa3b, v44
	v_exp_f32_e32 v49, v40
	v_pk_mul_f32 v[32:33], v[32:33], v[50:51]
	v_exp_f32_e32 v35, v35
	v_pk_add_f32 v[48:49], v[48:49], 1.0 op_sel_hi:[1,0]
	s_nop 0
	v_rcp_f32_e32 v50, v49
	v_pk_add_f32 v[34:35], v[34:35], 1.0 op_sel_hi:[1,0]
	v_mul_f32_e32 v40, v44, v50
	v_mov_b32_e32 v49, v40
	v_rcp_f32_e32 v44, v48
	s_nop 0
	v_mul_f32_e32 v40, v52, v44
	v_mov_b32_e32 v48, v40
	v_pk_mul_f32 v[32:33], v[48:49], v[32:33]
	v_and_b32_e32 v48, 0xffff0000, v181
	v_cvt_pk_bf16_f32 v32, v32, v33
	v_mul_f32_e32 v33, 0xbfb8aa3b, v38
	v_exp_f32_e32 v38, v33
	v_mul_f32_e32 v33, 0xbfb8aa3b, v39
	v_exp_f32_e32 v39, v33
	v_lshlrev_b32_e32 v33, 16, v181
	v_lshlrev_b32_e32 v44, 16, v177
	v_and_b32_e32 v45, 0xffff0000, v177
	v_pk_add_f32 v[38:39], v[38:39], 1.0 op_sel_hi:[1,0]
	v_mul_f32_e32 v40, 0xbfb8aa3b, v33
	v_rcp_f32_e32 v49, v39
	v_exp_f32_e32 v40, v40
	v_mul_f32_e32 v41, 1.0, v49
	v_mov_b32_e32 v39, v41
	v_rcp_f32_e32 v49, v38
	s_nop 0
	v_mul_f32_e32 v41, 1.0, v49
	v_mov_b32_e32 v38, v41
	v_mul_f32_e32 v41, 0xbfb8aa3b, v48
	v_exp_f32_e32 v41, v41
	v_pk_mul_f32 v[38:39], v[38:39], v[44:45]
	v_pk_add_f32 v[40:41], v[40:41], 1.0 op_sel_hi:[1,0]
	s_nop 0
	v_rcp_f32_e32 v45, v41
	s_nop 0
	v_mul_f32_e32 v44, v48, v45
	v_mov_b32_e32 v41, v44
	v_rcp_f32_e32 v45, v40
	s_nop 0
	v_mul_f32_e32 v44, v33, v45
	v_mov_b32_e32 v40, v44
	v_pk_mul_f32 v[38:39], v[40:41], v[38:39]
	v_lshlrev_b32_e32 v40, 16, v178
	v_cvt_pk_bf16_f32 v33, v38, v39
	v_and_b32_e32 v41, 0xffff0000, v178
	v_rcp_f32_e32 v42, v35
	v_lshlrev_b32_e32 v44, 16, v182
	v_and_b32_e32 v45, 0xffff0000, v182
	v_mul_f32_e32 v38, 0xbfb8aa3b, v44
	v_mul_f32_e32 v39, 1.0, v42
	v_mov_b32_e32 v35, v39
	v_rcp_f32_e32 v42, v34
	v_exp_f32_e32 v38, v38
	v_mul_f32_e32 v39, 1.0, v42
	v_mov_b32_e32 v34, v39
	v_mul_f32_e32 v39, 0xbfb8aa3b, v45
	v_exp_f32_e32 v39, v39
	v_pk_mul_f32 v[34:35], v[34:35], v[40:41]
	v_pk_add_f32 v[38:39], v[38:39], 1.0 op_sel_hi:[1,0]
	s_nop 0
	v_rcp_f32_e32 v41, v39
	s_nop 0
	v_mul_f32_e32 v40, v45, v41
	v_mov_b32_e32 v39, v40
	v_rcp_f32_e32 v41, v38
	s_nop 0
	v_mul_f32_e32 v40, v44, v41
	v_mov_b32_e32 v38, v40
	v_pk_mul_f32 v[34:35], v[38:39], v[34:35]
	v_lshlrev_b32_e32 v40, 16, v179
	v_cvt_pk_bf16_f32 v34, v34, v35
	v_mul_f32_e32 v35, 0xbfb8aa3b, v36
	v_exp_f32_e32 v36, v35
	v_mul_f32_e32 v35, 0xbfb8aa3b, v37
	v_exp_f32_e32 v37, v35
	v_and_b32_e32 v41, 0xffff0000, v179
	v_lshlrev_b32_e32 v35, 16, v183
	v_and_b32_e32 v42, 0xffff0000, v183
	v_pk_add_f32 v[36:37], v[36:37], 1.0 op_sel_hi:[1,0]
	v_mul_f32_e32 v38, 0xbfb8aa3b, v35
	v_rcp_f32_e32 v43, v37
	v_exp_f32_e32 v38, v38
	v_mul_f32_e32 v39, 1.0, v43
	v_mov_b32_e32 v37, v39
	v_rcp_f32_e32 v43, v36
	s_nop 0
	v_mul_f32_e32 v39, 1.0, v43
	v_mov_b32_e32 v36, v39
	v_mul_f32_e32 v39, 0xbfb8aa3b, v42
	v_exp_f32_e32 v39, v39
	v_pk_mul_f32 v[36:37], v[36:37], v[40:41]
	v_pk_add_f32 v[38:39], v[38:39], 1.0 op_sel_hi:[1,0]
	s_nop 0
	v_rcp_f32_e32 v41, v39
	s_nop 0
	v_mul_f32_e32 v40, v42, v41
	v_mov_b32_e32 v39, v40
	v_rcp_f32_e32 v41, v38
	s_nop 0
	v_mul_f32_e32 v40, v35, v41
	v_mov_b32_e32 v38, v40
	v_pk_mul_f32 v[36:37], v[38:39], v[36:37]
	s_nop 0
	v_cvt_pk_bf16_f32 v35, v36, v37
	global_store_dwordx4 v[250:251], v[32:35], off offset:256
	global_load_dwordx4 v[176:179], v[246:247], off offset:256
	global_load_dwordx4 v[180:183], v[214:215], off offset:256
	global_load_dwordx4 v[184:187], v[142:143], off offset:528
	global_load_dwordx4 v[208:211], v[142:143], off offset:512
	s_waitcnt vmcnt(5)
	v_pk_add_f32 v[46:47], v[26:27], v[238:239]
	v_pk_add_f32 v[28:29], v[28:29], v[240:241]
	v_pk_add_f32 v[26:27], v[24:25], v[236:237]
	v_mul_f32_e32 v24, 0xbfb8aa3b, v28
	v_mul_f32_e32 v25, 0xbfb8aa3b, v29
	v_exp_f32_e32 v24, v24
	v_exp_f32_e32 v25, v25
	v_lshlrev_b32_e32 v44, 16, v228
	v_and_b32_e32 v45, 0xffff0000, v228
	v_pk_add_f32 v[30:31], v[30:31], v[242:243]
	v_pk_add_f32 v[24:25], v[24:25], 1.0 op_sel_hi:[1,0]
	v_lshlrev_b32_e32 v48, 16, v232
	v_rcp_f32_e32 v32, v25
	v_and_b32_e32 v36, 0xffff0000, v232
	v_mul_f32_e32 v28, 0xbfb8aa3b, v48
	v_exp_f32_e32 v28, v28
	v_mul_f32_e32 v29, 1.0, v32
	v_mov_b32_e32 v25, v29
	v_rcp_f32_e32 v32, v24
	v_mul_f32_e32 v26, 0xbfb8aa3b, v26
	v_mul_f32_e32 v27, 0xbfb8aa3b, v27
	v_exp_f32_e32 v26, v26
	v_mul_f32_e32 v29, 1.0, v32
	v_mov_b32_e32 v24, v29
	v_mul_f32_e32 v29, 0xbfb8aa3b, v36
	v_exp_f32_e32 v29, v29
	v_pk_mul_f32 v[24:25], v[24:25], v[44:45]
	v_exp_f32_e32 v27, v27
	v_pk_add_f32 v[28:29], v[28:29], 1.0 op_sel_hi:[1,0]
	s_nop 0
	v_rcp_f32_e32 v44, v29
	v_pk_add_f32 v[26:27], v[26:27], 1.0 op_sel_hi:[1,0]
	v_mul_f32_e32 v32, v36, v44
	v_mov_b32_e32 v29, v32
	v_rcp_f32_e32 v36, v28
	s_nop 0
	v_mul_f32_e32 v32, v48, v36
	v_mov_b32_e32 v28, v32
	v_pk_mul_f32 v[24:25], v[28:29], v[24:25]
	v_and_b32_e32 v36, 0xffff0000, v233
	v_cvt_pk_bf16_f32 v24, v24, v25
	v_mul_f32_e32 v25, 0xbfb8aa3b, v30
	v_exp_f32_e32 v28, v25
	v_mul_f32_e32 v25, 0xbfb8aa3b, v31
	v_exp_f32_e32 v29, v25
	v_lshlrev_b32_e32 v25, 16, v233
	v_mul_f32_e32 v30, 0xbfb8aa3b, v25
	v_exp_f32_e32 v30, v30
	v_pk_add_f32 v[28:29], v[28:29], 1.0 op_sel_hi:[1,0]
	v_lshlrev_b32_e32 v32, 16, v229
	v_rcp_f32_e32 v37, v29
	v_and_b32_e32 v33, 0xffff0000, v229
	v_mul_f32_e32 v31, 1.0, v37
	v_mov_b32_e32 v29, v31
	v_rcp_f32_e32 v37, v28
	s_nop 0
	v_mul_f32_e32 v31, 1.0, v37
	v_mov_b32_e32 v28, v31
	v_mul_f32_e32 v31, 0xbfb8aa3b, v36
	v_exp_f32_e32 v31, v31
	v_pk_mul_f32 v[28:29], v[28:29], v[32:33]
	v_pk_add_f32 v[30:31], v[30:31], 1.0 op_sel_hi:[1,0]
	s_nop 0
	v_rcp_f32_e32 v33, v31
	s_nop 0
	v_mul_f32_e32 v32, v36, v33
	v_mov_b32_e32 v31, v32
	v_rcp_f32_e32 v33, v30
	s_nop 0
	v_mul_f32_e32 v32, v25, v33
	v_mov_b32_e32 v30, v32
	v_pk_mul_f32 v[28:29], v[30:31], v[28:29]
	v_lshlrev_b32_e32 v30, 16, v230
	v_cvt_pk_bf16_f32 v25, v28, v29
	v_and_b32_e32 v31, 0xffff0000, v230
	v_rcp_f32_e32 v34, v27
	v_lshlrev_b32_e32 v32, 16, v234
	v_and_b32_e32 v33, 0xffff0000, v234
	v_mul_f32_e32 v28, 0xbfb8aa3b, v32
	v_mul_f32_e32 v29, 1.0, v34
	v_mov_b32_e32 v27, v29
	v_rcp_f32_e32 v34, v26
	v_exp_f32_e32 v28, v28
	v_mul_f32_e32 v29, 1.0, v34
	v_mov_b32_e32 v26, v29
	v_mul_f32_e32 v29, 0xbfb8aa3b, v33
	v_exp_f32_e32 v29, v29
	v_pk_mul_f32 v[26:27], v[26:27], v[30:31]
	v_pk_add_f32 v[28:29], v[28:29], 1.0 op_sel_hi:[1,0]
	s_nop 0
	v_rcp_f32_e32 v31, v29
	s_nop 0
	v_mul_f32_e32 v30, v33, v31
	v_mov_b32_e32 v29, v30
	v_rcp_f32_e32 v31, v28
	s_nop 0
	v_mul_f32_e32 v30, v32, v31
	v_mov_b32_e32 v28, v30
	v_pk_mul_f32 v[26:27], v[28:29], v[26:27]
	v_lshlrev_b32_e32 v32, 16, v231
	v_cvt_pk_bf16_f32 v26, v26, v27
	v_mul_f32_e32 v27, 0xbfb8aa3b, v46
	v_exp_f32_e32 v28, v27
	v_mul_f32_e32 v27, 0xbfb8aa3b, v47
	v_exp_f32_e32 v29, v27
	v_and_b32_e32 v33, 0xffff0000, v231
	v_lshlrev_b32_e32 v27, 16, v235
	v_and_b32_e32 v34, 0xffff0000, v235
	v_pk_add_f32 v[28:29], v[28:29], 1.0 op_sel_hi:[1,0]
	v_mul_f32_e32 v30, 0xbfb8aa3b, v27
	v_rcp_f32_e32 v35, v29
	v_exp_f32_e32 v30, v30
	v_mul_f32_e32 v31, 1.0, v35
	v_mov_b32_e32 v29, v31
	v_rcp_f32_e32 v35, v28
	s_nop 0
	v_mul_f32_e32 v31, 1.0, v35
	v_mov_b32_e32 v28, v31
	v_mul_f32_e32 v31, 0xbfb8aa3b, v34
	v_exp_f32_e32 v31, v31
	v_pk_mul_f32 v[28:29], v[28:29], v[32:33]
	v_pk_add_f32 v[30:31], v[30:31], 1.0 op_sel_hi:[1,0]
	s_nop 0
	v_rcp_f32_e32 v33, v31
	s_nop 0
	v_mul_f32_e32 v32, v34, v33
	v_mov_b32_e32 v31, v32
	v_rcp_f32_e32 v33, v30
	s_nop 0
	v_mul_f32_e32 v32, v27, v33
	v_mov_b32_e32 v30, v32
	v_pk_mul_f32 v[28:29], v[30:31], v[28:29]
	s_nop 0
	v_cvt_pk_bf16_f32 v27, v28, v29
	global_store_dwordx4 v[214:215], v[24:27], off
	s_nop 1
	v_add_u32_e32 v248, 0xb0, v154
	v_mad_i64_i32 v[248:249], s[0:1], v248, s14, v[144:145]
	v_lshl_add_u64 v[250:251], v[248:249], 0, v[146:147]
	v_add_co_u32_e32 v174, vcc, s15, v250
	s_nop 1
	v_addc_co_u32_e32 v175, vcc, 0, v251, vcc
	global_load_dwordx4 v[228:231], v[174:175], off
	global_load_dwordx4 v[232:235], v[250:251], off
	global_load_dwordx4 v[236:239], v[142:143], off offset:16
	global_load_dwordx4 v[240:243], v[142:143], off
	s_waitcnt vmcnt(5)
	v_pk_add_f32 v[36:37], v[20:21], v[208:209]
	v_pk_add_f32 v[20:21], v[18:19], v[186:187]
	v_pk_add_f32 v[18:19], v[16:17], v[184:185]
	v_mul_f32_e32 v16, 0xbfb8aa3b, v36
	v_mul_f32_e32 v17, 0xbfb8aa3b, v37
	v_exp_f32_e32 v16, v16
	v_exp_f32_e32 v17, v17
	v_lshlrev_b32_e32 v34, 16, v176
	v_and_b32_e32 v35, 0xffff0000, v176
	v_pk_add_f32 v[22:23], v[22:23], v[210:211]
	v_pk_add_f32 v[16:17], v[16:17], 1.0 op_sel_hi:[1,0]
	v_lshlrev_b32_e32 v36, 16, v180
	v_rcp_f32_e32 v33, v17
	v_and_b32_e32 v28, 0xffff0000, v180
	v_mul_f32_e32 v32, 0xbfb8aa3b, v36
	v_exp_f32_e32 v32, v32
	v_mul_f32_e32 v24, 1.0, v33
	v_mov_b32_e32 v17, v24
	v_rcp_f32_e32 v33, v16
	v_mul_f32_e32 v18, 0xbfb8aa3b, v18
	v_mul_f32_e32 v19, 0xbfb8aa3b, v19
	v_exp_f32_e32 v18, v18
	v_mul_f32_e32 v24, 1.0, v33
	v_mov_b32_e32 v16, v24
	v_mul_f32_e32 v24, 0xbfb8aa3b, v28
	v_exp_f32_e32 v33, v24
	v_pk_mul_f32 v[16:17], v[16:17], v[34:35]
	v_exp_f32_e32 v19, v19
	v_pk_add_f32 v[32:33], v[32:33], 1.0 op_sel_hi:[1,0]
	s_nop 0
	v_rcp_f32_e32 v34, v33
	v_pk_add_f32 v[18:19], v[18:19], 1.0 op_sel_hi:[1,0]
	v_mul_f32_e32 v24, v28, v34
	v_mov_b32_e32 v33, v24
	v_rcp_f32_e32 v28, v32
	s_nop 0
	v_mul_f32_e32 v24, v36, v28
	v_mov_b32_e32 v32, v24
	v_pk_mul_f32 v[16:17], v[32:33], v[16:17]
	v_and_b32_e32 v32, 0xffff0000, v181
	v_cvt_pk_bf16_f32 v16, v16, v17
	v_mul_f32_e32 v17, 0xbfb8aa3b, v22
	v_exp_f32_e32 v22, v17
	v_mul_f32_e32 v17, 0xbfb8aa3b, v23
	v_exp_f32_e32 v23, v17
	v_lshlrev_b32_e32 v17, 16, v181
	v_lshlrev_b32_e32 v28, 16, v177
	v_and_b32_e32 v29, 0xffff0000, v177
	v_pk_add_f32 v[22:23], v[22:23], 1.0 op_sel_hi:[1,0]
	v_mul_f32_e32 v24, 0xbfb8aa3b, v17
	v_rcp_f32_e32 v33, v23
	v_exp_f32_e32 v24, v24
	v_mul_f32_e32 v25, 1.0, v33
	v_mov_b32_e32 v23, v25
	v_rcp_f32_e32 v33, v22
	s_nop 0
	v_mul_f32_e32 v25, 1.0, v33
	v_mov_b32_e32 v22, v25
	v_mul_f32_e32 v25, 0xbfb8aa3b, v32
	v_exp_f32_e32 v25, v25
	v_pk_mul_f32 v[22:23], v[22:23], v[28:29]
	v_pk_add_f32 v[24:25], v[24:25], 1.0 op_sel_hi:[1,0]
	s_nop 0
	v_rcp_f32_e32 v29, v25
	s_nop 0
	v_mul_f32_e32 v28, v32, v29
	v_mov_b32_e32 v25, v28
	v_rcp_f32_e32 v29, v24
	s_nop 0
	v_mul_f32_e32 v28, v17, v29
	v_mov_b32_e32 v24, v28
	v_pk_mul_f32 v[22:23], v[24:25], v[22:23]
	v_lshlrev_b32_e32 v24, 16, v178
	v_cvt_pk_bf16_f32 v17, v22, v23
	v_and_b32_e32 v25, 0xffff0000, v178
	v_rcp_f32_e32 v26, v19
	v_lshlrev_b32_e32 v28, 16, v182
	v_and_b32_e32 v29, 0xffff0000, v182
	v_mul_f32_e32 v22, 0xbfb8aa3b, v28
	v_mul_f32_e32 v23, 1.0, v26
	v_mov_b32_e32 v19, v23
	v_rcp_f32_e32 v26, v18
	v_exp_f32_e32 v22, v22
	v_mul_f32_e32 v23, 1.0, v26
	v_mov_b32_e32 v18, v23
	v_mul_f32_e32 v23, 0xbfb8aa3b, v29
	v_exp_f32_e32 v23, v23
	v_pk_mul_f32 v[18:19], v[18:19], v[24:25]
	v_pk_add_f32 v[22:23], v[22:23], 1.0 op_sel_hi:[1,0]
	s_nop 0
	v_rcp_f32_e32 v25, v23
	s_nop 0
	v_mul_f32_e32 v24, v29, v25
	v_mov_b32_e32 v23, v24
	v_rcp_f32_e32 v25, v22
	s_nop 0
	v_mul_f32_e32 v24, v28, v25
	v_mov_b32_e32 v22, v24
	v_pk_mul_f32 v[18:19], v[22:23], v[18:19]
	v_lshlrev_b32_e32 v24, 16, v179
	v_cvt_pk_bf16_f32 v18, v18, v19
	v_mul_f32_e32 v19, 0xbfb8aa3b, v20
	v_exp_f32_e32 v20, v19
	v_mul_f32_e32 v19, 0xbfb8aa3b, v21
	v_exp_f32_e32 v21, v19
	v_and_b32_e32 v25, 0xffff0000, v179
	v_lshlrev_b32_e32 v19, 16, v183
	v_and_b32_e32 v26, 0xffff0000, v183
	v_pk_add_f32 v[20:21], v[20:21], 1.0 op_sel_hi:[1,0]
	v_mul_f32_e32 v22, 0xbfb8aa3b, v19
	v_rcp_f32_e32 v27, v21
	v_exp_f32_e32 v22, v22
	v_mul_f32_e32 v23, 1.0, v27
	v_mov_b32_e32 v21, v23
	v_rcp_f32_e32 v27, v20
	s_nop 0
	v_mul_f32_e32 v23, 1.0, v27
	v_mov_b32_e32 v20, v23
	v_mul_f32_e32 v23, 0xbfb8aa3b, v26
	v_exp_f32_e32 v23, v23
	v_pk_mul_f32 v[20:21], v[20:21], v[24:25]
	v_pk_add_f32 v[22:23], v[22:23], 1.0 op_sel_hi:[1,0]
	s_nop 0
	v_rcp_f32_e32 v25, v23
	s_nop 0
	v_mul_f32_e32 v24, v26, v25
	v_mov_b32_e32 v23, v24
	v_rcp_f32_e32 v25, v22
	s_nop 0
	v_mul_f32_e32 v24, v19, v25
	v_mov_b32_e32 v22, v24
	v_pk_mul_f32 v[20:21], v[22:23], v[20:21]
	s_nop 0
	v_cvt_pk_bf16_f32 v19, v20, v21
	global_store_dwordx4 v[214:215], v[16:19], off offset:256
	global_load_dwordx4 v[176:179], v[174:175], off offset:256
	global_load_dwordx4 v[180:183], v[250:251], off offset:256
	global_load_dwordx4 v[184:187], v[142:143], off offset:528
	global_load_dwordx4 v[208:211], v[142:143], off offset:512
	s_waitcnt vmcnt(5)
	v_pk_add_f32 v[30:31], v[10:11], v[238:239]
	v_pk_add_f32 v[12:13], v[12:13], v[240:241]
	v_pk_add_f32 v[10:11], v[8:9], v[236:237]
	v_mul_f32_e32 v8, 0xbfb8aa3b, v12
	v_mul_f32_e32 v9, 0xbfb8aa3b, v13
	v_exp_f32_e32 v8, v8
	v_exp_f32_e32 v9, v9
	v_lshlrev_b32_e32 v28, 16, v228
	v_and_b32_e32 v29, 0xffff0000, v228
	v_pk_add_f32 v[14:15], v[14:15], v[242:243]
	v_pk_add_f32 v[8:9], v[8:9], 1.0 op_sel_hi:[1,0]
	v_lshlrev_b32_e32 v32, 16, v232
	v_rcp_f32_e32 v16, v9
	v_and_b32_e32 v20, 0xffff0000, v232
	v_mul_f32_e32 v12, 0xbfb8aa3b, v32
	v_exp_f32_e32 v12, v12
	v_mul_f32_e32 v13, 1.0, v16
	v_mov_b32_e32 v9, v13
	v_rcp_f32_e32 v16, v8
	v_mul_f32_e32 v10, 0xbfb8aa3b, v10
	v_mul_f32_e32 v11, 0xbfb8aa3b, v11
	v_exp_f32_e32 v10, v10
	v_mul_f32_e32 v13, 1.0, v16
	v_mov_b32_e32 v8, v13
	v_mul_f32_e32 v13, 0xbfb8aa3b, v20
	v_exp_f32_e32 v13, v13
	v_pk_mul_f32 v[8:9], v[8:9], v[28:29]
	v_exp_f32_e32 v11, v11
	v_pk_add_f32 v[12:13], v[12:13], 1.0 op_sel_hi:[1,0]
	s_nop 0
	v_rcp_f32_e32 v28, v13
	v_pk_add_f32 v[10:11], v[10:11], 1.0 op_sel_hi:[1,0]
	v_mul_f32_e32 v16, v20, v28
	v_mov_b32_e32 v13, v16
	v_rcp_f32_e32 v20, v12
	s_nop 0
	v_mul_f32_e32 v16, v32, v20
	v_mov_b32_e32 v12, v16
	v_pk_mul_f32 v[8:9], v[12:13], v[8:9]
	v_and_b32_e32 v20, 0xffff0000, v233
	v_cvt_pk_bf16_f32 v8, v8, v9
	v_mul_f32_e32 v9, 0xbfb8aa3b, v14
	v_exp_f32_e32 v12, v9
	v_mul_f32_e32 v9, 0xbfb8aa3b, v15
	v_exp_f32_e32 v13, v9
	v_lshlrev_b32_e32 v9, 16, v233
	v_mul_f32_e32 v14, 0xbfb8aa3b, v9
	v_exp_f32_e32 v14, v14
	v_pk_add_f32 v[12:13], v[12:13], 1.0 op_sel_hi:[1,0]
	v_lshlrev_b32_e32 v16, 16, v229
	v_rcp_f32_e32 v21, v13
	v_and_b32_e32 v17, 0xffff0000, v229
	v_mul_f32_e32 v15, 1.0, v21
	v_mov_b32_e32 v13, v15
	v_rcp_f32_e32 v21, v12
	s_nop 0
	v_mul_f32_e32 v15, 1.0, v21
	v_mov_b32_e32 v12, v15
	v_mul_f32_e32 v15, 0xbfb8aa3b, v20
	v_exp_f32_e32 v15, v15
	v_pk_mul_f32 v[12:13], v[12:13], v[16:17]
	v_pk_add_f32 v[14:15], v[14:15], 1.0 op_sel_hi:[1,0]
	s_nop 0
	v_rcp_f32_e32 v17, v15
	s_nop 0
	v_mul_f32_e32 v16, v20, v17
	v_mov_b32_e32 v15, v16
	v_rcp_f32_e32 v17, v14
	s_nop 0
	v_mul_f32_e32 v16, v9, v17
	v_mov_b32_e32 v14, v16
	v_pk_mul_f32 v[12:13], v[14:15], v[12:13]
	v_lshlrev_b32_e32 v14, 16, v230
	v_cvt_pk_bf16_f32 v9, v12, v13
	v_and_b32_e32 v15, 0xffff0000, v230
	v_rcp_f32_e32 v18, v11
	v_lshlrev_b32_e32 v16, 16, v234
	v_and_b32_e32 v17, 0xffff0000, v234
	v_mul_f32_e32 v12, 0xbfb8aa3b, v16
	v_mul_f32_e32 v13, 1.0, v18
	v_mov_b32_e32 v11, v13
	v_rcp_f32_e32 v18, v10
	v_exp_f32_e32 v12, v12
	v_mul_f32_e32 v13, 1.0, v18
	v_mov_b32_e32 v10, v13
	v_mul_f32_e32 v13, 0xbfb8aa3b, v17
	v_exp_f32_e32 v13, v13
	v_pk_mul_f32 v[10:11], v[10:11], v[14:15]
	v_pk_add_f32 v[12:13], v[12:13], 1.0 op_sel_hi:[1,0]
	s_nop 0
	v_rcp_f32_e32 v15, v13
	s_nop 0
	v_mul_f32_e32 v14, v17, v15
	v_mov_b32_e32 v13, v14
	v_rcp_f32_e32 v15, v12
	s_nop 0
	v_mul_f32_e32 v14, v16, v15
	v_mov_b32_e32 v12, v14
	v_pk_mul_f32 v[10:11], v[12:13], v[10:11]
	v_lshlrev_b32_e32 v16, 16, v231
	v_cvt_pk_bf16_f32 v10, v10, v11
	v_mul_f32_e32 v11, 0xbfb8aa3b, v30
	v_exp_f32_e32 v12, v11
	v_mul_f32_e32 v11, 0xbfb8aa3b, v31
	v_exp_f32_e32 v13, v11
	v_and_b32_e32 v17, 0xffff0000, v231
	v_lshlrev_b32_e32 v11, 16, v235
	v_and_b32_e32 v18, 0xffff0000, v235
	v_pk_add_f32 v[12:13], v[12:13], 1.0 op_sel_hi:[1,0]
	v_mul_f32_e32 v14, 0xbfb8aa3b, v11
	v_rcp_f32_e32 v19, v13
	v_exp_f32_e32 v14, v14
	v_mul_f32_e32 v15, 1.0, v19
	v_mov_b32_e32 v13, v15
	v_rcp_f32_e32 v19, v12
	s_nop 0
	v_mul_f32_e32 v15, 1.0, v19
	v_mov_b32_e32 v12, v15
	v_mul_f32_e32 v15, 0xbfb8aa3b, v18
	v_exp_f32_e32 v15, v15
	v_pk_mul_f32 v[12:13], v[12:13], v[16:17]
	v_pk_add_f32 v[14:15], v[14:15], 1.0 op_sel_hi:[1,0]
	s_nop 0
	v_rcp_f32_e32 v17, v15
	s_nop 0
	v_mul_f32_e32 v16, v18, v17
	v_mov_b32_e32 v15, v16
	v_rcp_f32_e32 v17, v14
	s_nop 0
	v_mul_f32_e32 v16, v11, v17
	v_mov_b32_e32 v14, v16
	v_pk_mul_f32 v[12:13], v[14:15], v[12:13]
	s_nop 0
	v_cvt_pk_bf16_f32 v11, v12, v13
	global_store_dwordx4 v[250:251], v[8:11], off
	s_waitcnt vmcnt(1)
	v_pk_add_f32 v[20:21], v[4:5], v[208:209]
	v_pk_add_f32 v[4:5], v[2:3], v[186:187]
	v_pk_add_f32 v[2:3], v[0:1], v[184:185]
	v_mul_f32_e32 v0, 0xbfb8aa3b, v20
	v_mul_f32_e32 v1, 0xbfb8aa3b, v21
	v_exp_f32_e32 v0, v0
	v_exp_f32_e32 v1, v1
	v_lshlrev_b32_e32 v18, 16, v176
	v_and_b32_e32 v19, 0xffff0000, v176
	v_pk_add_f32 v[6:7], v[6:7], v[210:211]
	v_pk_add_f32 v[0:1], v[0:1], 1.0 op_sel_hi:[1,0]
	v_lshlrev_b32_e32 v20, 16, v180
	v_rcp_f32_e32 v17, v1
	v_and_b32_e32 v12, 0xffff0000, v180
	v_mul_f32_e32 v16, 0xbfb8aa3b, v20
	v_exp_f32_e32 v16, v16
	v_mul_f32_e32 v8, 1.0, v17
	v_mov_b32_e32 v1, v8
	v_rcp_f32_e32 v17, v0
	v_mul_f32_e32 v2, 0xbfb8aa3b, v2
	v_mul_f32_e32 v3, 0xbfb8aa3b, v3
	v_exp_f32_e32 v2, v2
	v_mul_f32_e32 v8, 1.0, v17
	v_mov_b32_e32 v0, v8
	v_mul_f32_e32 v8, 0xbfb8aa3b, v12
	v_exp_f32_e32 v17, v8
	v_pk_mul_f32 v[0:1], v[0:1], v[18:19]
	v_exp_f32_e32 v3, v3
	v_pk_add_f32 v[16:17], v[16:17], 1.0 op_sel_hi:[1,0]
	s_nop 0
	v_rcp_f32_e32 v18, v17
	v_pk_add_f32 v[2:3], v[2:3], 1.0 op_sel_hi:[1,0]
	v_mul_f32_e32 v8, v12, v18
	v_mov_b32_e32 v17, v8
	v_rcp_f32_e32 v12, v16
	s_nop 0
	v_mul_f32_e32 v8, v20, v12
	v_mov_b32_e32 v16, v8
	v_pk_mul_f32 v[0:1], v[16:17], v[0:1]
	v_and_b32_e32 v16, 0xffff0000, v181
	v_cvt_pk_bf16_f32 v0, v0, v1
	v_mul_f32_e32 v1, 0xbfb8aa3b, v6
	v_exp_f32_e32 v6, v1
	v_mul_f32_e32 v1, 0xbfb8aa3b, v7
	v_exp_f32_e32 v7, v1
	v_lshlrev_b32_e32 v1, 16, v181
	v_lshlrev_b32_e32 v12, 16, v177
	v_and_b32_e32 v13, 0xffff0000, v177
	v_pk_add_f32 v[6:7], v[6:7], 1.0 op_sel_hi:[1,0]
	v_mul_f32_e32 v8, 0xbfb8aa3b, v1
	v_rcp_f32_e32 v17, v7
	v_exp_f32_e32 v8, v8
	v_mul_f32_e32 v9, 1.0, v17
	v_mov_b32_e32 v7, v9
	v_rcp_f32_e32 v17, v6
	s_nop 0
	v_mul_f32_e32 v9, 1.0, v17
	v_mov_b32_e32 v6, v9
	v_mul_f32_e32 v9, 0xbfb8aa3b, v16
	v_exp_f32_e32 v9, v9
	v_pk_mul_f32 v[6:7], v[6:7], v[12:13]
	v_pk_add_f32 v[8:9], v[8:9], 1.0 op_sel_hi:[1,0]
	s_nop 0
	v_rcp_f32_e32 v13, v9
	s_nop 0
	v_mul_f32_e32 v12, v16, v13
	v_mov_b32_e32 v9, v12
	v_rcp_f32_e32 v13, v8
	s_nop 0
	v_mul_f32_e32 v12, v1, v13
	v_mov_b32_e32 v8, v12
	v_pk_mul_f32 v[6:7], v[8:9], v[6:7]
	v_lshlrev_b32_e32 v8, 16, v178
	v_cvt_pk_bf16_f32 v1, v6, v7
	v_and_b32_e32 v9, 0xffff0000, v178
	v_rcp_f32_e32 v10, v3
	v_lshlrev_b32_e32 v12, 16, v182
	v_and_b32_e32 v13, 0xffff0000, v182
	v_mul_f32_e32 v6, 0xbfb8aa3b, v12
	v_mul_f32_e32 v7, 1.0, v10
	v_mov_b32_e32 v3, v7
	v_rcp_f32_e32 v10, v2
	v_exp_f32_e32 v6, v6
	v_mul_f32_e32 v7, 1.0, v10
	v_mov_b32_e32 v2, v7
	v_mul_f32_e32 v7, 0xbfb8aa3b, v13
	v_exp_f32_e32 v7, v7
	v_pk_mul_f32 v[2:3], v[2:3], v[8:9]
	v_pk_add_f32 v[6:7], v[6:7], 1.0 op_sel_hi:[1,0]
	s_nop 0
	v_rcp_f32_e32 v9, v7
	s_nop 0
	v_mul_f32_e32 v8, v13, v9
	v_mov_b32_e32 v7, v8
	v_rcp_f32_e32 v9, v6
	s_nop 0
	v_mul_f32_e32 v8, v12, v9
	v_mov_b32_e32 v6, v8
	v_pk_mul_f32 v[2:3], v[6:7], v[2:3]
	v_lshlrev_b32_e32 v8, 16, v179
	v_cvt_pk_bf16_f32 v2, v2, v3
	v_mul_f32_e32 v3, 0xbfb8aa3b, v4
	v_exp_f32_e32 v4, v3
	v_mul_f32_e32 v3, 0xbfb8aa3b, v5
	v_exp_f32_e32 v5, v3
	v_and_b32_e32 v9, 0xffff0000, v179
	v_lshlrev_b32_e32 v3, 16, v183
	v_and_b32_e32 v10, 0xffff0000, v183
	v_pk_add_f32 v[4:5], v[4:5], 1.0 op_sel_hi:[1,0]
	v_mul_f32_e32 v6, 0xbfb8aa3b, v3
	v_rcp_f32_e32 v11, v5
	v_exp_f32_e32 v6, v6
	v_mul_f32_e32 v7, 1.0, v11
	v_mov_b32_e32 v5, v7
	v_rcp_f32_e32 v11, v4
	s_nop 0
	v_mul_f32_e32 v7, 1.0, v11
	v_mov_b32_e32 v4, v7
	v_mul_f32_e32 v7, 0xbfb8aa3b, v10
	v_exp_f32_e32 v7, v7
	v_pk_mul_f32 v[4:5], v[4:5], v[8:9]
	v_pk_add_f32 v[6:7], v[6:7], 1.0 op_sel_hi:[1,0]
	s_nop 0
	v_rcp_f32_e32 v9, v7
	s_nop 0
	v_mul_f32_e32 v8, v10, v9
	v_mov_b32_e32 v7, v8
	v_rcp_f32_e32 v9, v6
	s_mov_b64 s[0:1], -1
	v_mul_f32_e32 v8, v3, v9
	v_mov_b32_e32 v6, v8
	v_pk_mul_f32 v[4:5], v[6:7], v[4:5]
	s_and_b64 vcc, exec, s[38:39]
	v_cvt_pk_bf16_f32 v3, v4, v5
	global_store_dwordx4 v[250:251], v[0:3], off offset:256
	s_cbranch_vccnz .LBB0_903
	s_andn2_b64 vcc, exec, s[84:85]
	s_cbranch_vccnz .LBB0_902
	s_barrier
	s_branch .LBB0_902

.LBB0_1130:
	v_readlane_b32 s0, v253, 4
	v_readlane_b32 s1, v253, 5
	s_andn2_b64 vcc, exec, s[0:1]
	v_readlane_b32 s16, v253, 12
	v_readlane_b32 s18, v253, 6
	v_readlane_b32 s17, v253, 13
	s_cbranch_vccnz .LBB0_1145
	v_readlane_b32 s0, v252, 52
	v_readlane_b32 s1, v252, 53
	s_mov_b32 s0, 0
	v_readlane_b32 s2, v252, 54
	v_readlane_b32 s3, v252, 55
	s_mov_b32 s1, s0
	v_mov_b32_e32 v189, 0
	v_readlane_b32 s12, v253, 0
	v_readlane_b32 s13, v253, 1
	v_readlane_b32 s14, v253, 2
	v_readlane_b32 s15, v253, 3
	s_mov_b32 s2, s0
	s_mov_b32 s3, s0
	v_mov_b64_e32 v[0:1], s[0:1]
	s_waitcnt vmcnt(1)
	v_lshl_add_u64 v[68:69], s[80:81], 0, v[188:189]
	v_lshl_add_u64 v[70:71], s[14:15], 0, v[188:189]
	global_load_dwordx4 v[96:99], v[70:71], off
	global_load_dwordx4 v[100:103], v[70:71], off offset:1024
	global_load_dwordx4 v[104:107], v[70:71], off offset:2048
	global_load_dwordx4 v[108:111], v[70:71], off offset:3072
	s_lshl_b32 s12, s94, 4
	v_mov_b64_e32 v[2:3], s[2:3]
	v_mov_b32_e32 v74, 0x358637bd
	s_mov_b32 s13, 0x800000
	v_readlane_b32 s4, v252, 56
	v_readlane_b32 s5, v252, 57
	v_readlane_b32 s6, v252, 58
	v_readlane_b32 s7, v252, 59
	v_readlane_b32 s8, v252, 60
	v_readlane_b32 s9, v252, 61
	v_readlane_b32 s10, v252, 62
	v_readlane_b32 s11, v252, 63
	s_branch .LBB0_1133

.LBB0_1139:
	s_waitcnt vmcnt(3)
	v_pk_mul_f32 v[64:65], v[0:1], v[64:65] op_sel_hi:[0,1]
	v_pk_mul_f32 v[66:67], v[0:1], v[66:67] op_sel_hi:[0,1]
	s_waitcnt vmcnt(2)
	v_pk_mul_f32 v[60:61], v[0:1], v[60:61] op_sel_hi:[0,1]
	v_pk_mul_f32 v[62:63], v[0:1], v[62:63] op_sel_hi:[0,1]
	s_waitcnt vmcnt(1)
	v_pk_mul_f32 v[56:57], v[0:1], v[56:57] op_sel_hi:[0,1]
	v_pk_mul_f32 v[58:59], v[0:1], v[58:59] op_sel_hi:[0,1]
	s_waitcnt vmcnt(0)
	v_pk_mul_f32 v[52:53], v[0:1], v[52:53] op_sel_hi:[0,1]
	v_pk_mul_f32 v[54:55], v[0:1], v[54:55] op_sel_hi:[0,1]
	s_andn2_b64 vcc, exec, s[2:3]
	v_pk_mul_f32 v[66:67], v[66:67], v[98:99]
	v_pk_mul_f32 v[64:65], v[64:65], v[96:97]
	global_store_dwordx4 v[72:73], v[64:67], off nt
	v_pk_mul_f32 v[62:63], v[62:63], v[102:103]
	v_pk_mul_f32 v[60:61], v[60:61], v[100:101]
	global_store_dwordx4 v[72:73], v[60:63], off offset:1024 nt
	v_pk_mul_f32 v[58:59], v[58:59], v[106:107]
	v_pk_mul_f32 v[56:57], v[56:57], v[104:105]
	global_store_dwordx4 v[72:73], v[56:59], off offset:2048 nt
	v_pk_mul_f32 v[54:55], v[54:55], v[110:111]
	v_pk_mul_f32 v[52:53], v[52:53], v[108:109]
	global_store_dwordx4 v[72:73], v[52:55], off offset:3072 nt
	s_cbranch_vccz .LBB0_1142
	s_andn2_b64 vcc, exec, s[6:7]
	s_cbranch_vccz .LBB0_1143

.LBB0_1142:
	s_ashr_i32 s1, s0, 31
	v_pk_mul_f32 v[56:57], v[0:1], v[48:49] op_sel:[1,0]
	v_pk_mul_f32 v[58:59], v[0:1], v[50:51] op_sel:[1,0]
	s_lshl_b64 s[0:1], s[0:1], 12
	v_lshl_add_u64 v[60:61], v[68:69], 0, s[0:1]
	v_pk_mul_f32 v[54:55], v[58:59], v[98:99]
	v_pk_mul_f32 v[52:53], v[56:57], v[96:97]
	global_store_dwordx4 v[60:61], v[52:55], off nt
	v_pk_mul_f32 v[56:57], v[0:1], v[44:45] op_sel:[1,0]
	v_pk_mul_f32 v[58:59], v[0:1], v[46:47] op_sel:[1,0]
	v_pk_mul_f32 v[52:53], v[56:57], v[100:101]
	v_pk_mul_f32 v[54:55], v[58:59], v[102:103]
	global_store_dwordx4 v[60:61], v[52:55], off offset:1024 nt
	v_pk_mul_f32 v[56:57], v[0:1], v[40:41] op_sel:[1,0]
	v_pk_mul_f32 v[58:59], v[0:1], v[42:43] op_sel:[1,0]
	v_pk_mul_f32 v[52:53], v[56:57], v[104:105]
	v_pk_mul_f32 v[54:55], v[58:59], v[106:107]
	global_store_dwordx4 v[60:61], v[52:55], off offset:2048 nt
	v_pk_mul_f32 v[56:57], v[0:1], v[36:37] op_sel:[1,0]
	v_pk_mul_f32 v[58:59], v[0:1], v[38:39] op_sel:[1,0]
	v_pk_mul_f32 v[52:53], v[56:57], v[108:109]
	v_pk_mul_f32 v[54:55], v[58:59], v[110:111]
	global_store_dwordx4 v[60:61], v[52:55], off offset:3072 nt
	s_andn2_b64 vcc, exec, s[6:7]
	s_cbranch_vccnz .LBB0_1141
.LBB0_1143:
	s_ashr_i32 s5, s4, 31
	v_pk_mul_f32 v[56:57], v[2:3], v[34:35] op_sel_hi:[0,1]
	v_pk_mul_f32 v[58:59], v[2:3], v[32:33] op_sel_hi:[0,1]
	s_lshl_b64 s[0:1], s[4:5], 12
	v_lshl_add_u64 v[60:61], v[68:69], 0, s[0:1]
	v_pk_mul_f32 v[54:55], v[56:57], v[98:99]
	v_pk_mul_f32 v[52:53], v[58:59], v[96:97]
	global_store_dwordx4 v[60:61], v[52:55], off nt
	v_pk_mul_f32 v[56:57], v[2:3], v[30:31] op_sel_hi:[0,1]
	v_pk_mul_f32 v[58:59], v[2:3], v[28:29] op_sel_hi:[0,1]
	v_pk_mul_f32 v[54:55], v[56:57], v[102:103]
	v_pk_mul_f32 v[52:53], v[58:59], v[100:101]
	global_store_dwordx4 v[60:61], v[52:55], off offset:1024 nt
	v_pk_mul_f32 v[56:57], v[2:3], v[26:27] op_sel_hi:[0,1]
	v_pk_mul_f32 v[58:59], v[2:3], v[24:25] op_sel_hi:[0,1]
	v_pk_mul_f32 v[54:55], v[56:57], v[106:107]
	v_pk_mul_f32 v[52:53], v[58:59], v[104:105]
	global_store_dwordx4 v[60:61], v[52:55], off offset:2048 nt
	v_pk_mul_f32 v[56:57], v[2:3], v[22:23] op_sel_hi:[0,1]
	v_pk_mul_f32 v[58:59], v[2:3], v[20:21] op_sel_hi:[0,1]
	v_pk_mul_f32 v[54:55], v[56:57], v[110:111]
	v_pk_mul_f32 v[52:53], v[58:59], v[108:109]
	global_store_dwordx4 v[60:61], v[52:55], off offset:3072 nt
	s_andn2_b64 vcc, exec, s[10:11]
	s_cbranch_vccnz .LBB0_1132
.LBB0_1144:
	s_ashr_i32 s9, s8, 31
	v_mov_b32_e32 v0, v3
	s_lshl_b64 s[0:1], s[8:9], 12
	v_pk_mul_f32 v[56:57], v[0:1], v[18:19] op_sel_hi:[0,1]
	v_pk_mul_f32 v[58:59], v[0:1], v[16:17] op_sel_hi:[0,1]
	v_lshl_add_u64 v[60:61], v[68:69], 0, s[0:1]
	v_pk_mul_f32 v[54:55], v[56:57], v[98:99]
	v_pk_mul_f32 v[52:53], v[58:59], v[96:97]
	global_store_dwordx4 v[60:61], v[52:55], off nt
	v_pk_mul_f32 v[56:57], v[0:1], v[14:15] op_sel_hi:[0,1]
	v_pk_mul_f32 v[58:59], v[0:1], v[12:13] op_sel_hi:[0,1]
	v_pk_mul_f32 v[54:55], v[56:57], v[102:103]
	v_pk_mul_f32 v[52:53], v[58:59], v[100:101]
	global_store_dwordx4 v[60:61], v[52:55], off offset:1024 nt
	v_pk_mul_f32 v[56:57], v[0:1], v[10:11] op_sel_hi:[0,1]
	v_pk_mul_f32 v[58:59], v[0:1], v[8:9] op_sel_hi:[0,1]
	v_pk_mul_f32 v[54:55], v[56:57], v[106:107]
	v_pk_mul_f32 v[52:53], v[58:59], v[104:105]
	global_store_dwordx4 v[60:61], v[52:55], off offset:2048 nt
	v_pk_mul_f32 v[56:57], v[0:1], v[6:7] op_sel_hi:[0,1]
	v_pk_mul_f32 v[58:59], v[0:1], v[4:5] op_sel_hi:[0,1]
	v_pk_mul_f32 v[54:55], v[56:57], v[110:111]
	v_pk_mul_f32 v[52:53], v[58:59], v[108:109]
	global_store_dwordx4 v[60:61], v[52:55], off offset:3072 nt
	s_branch .LBB0_1132
